# scan step: the six LDS operand reads issued back to back at the step head (not interleaved with the dot products) + compute waves staggered by wave index
# speedup vs baseline: 1.0552x; 1.0122x over previous
; #define SC_GET(X, t) do { const float* p = rec + (t) * 320; w##X = *(const f32x4*)p; a##X = *(const f32x4*)(p + 4); b##X = *(const f32x4*)(p + 8); k##X = *(const f32x4*)(p + 12); q##X = *(const f32x4*)(p + 16); \
;                 v##X = *(const f32x4*)(VVa + (t) * 64); } while (0)
; DI void scan_phase(unsigned char* lds, const Ctx& a, const Op& d, const int variant) {
;     ...
;             } else if (!(variant & 1)) {
;                 const float* base = (const float*)(lds + bi * SC_BUF);
;                 const float* rec = base + jg * 20; const float* VVa = base + 10240 + rA * 2;
;                 f32x4 wA, aA, bA, kA, qA, vA, wB, aB, bB, kB, qB, vB;
;     ...
;                 SC_GET(A, 0);
; #pragma unroll 2
;                 for (int t = 0; t < SC_T; t += 2) {
;                     SC_GET(B, t + 1);
;                     SC_STEP(A, t);
;                     if (t + 2 < SC_T) SC_GET(A, t + 2);
;                     SC_STEP(B, t + 1);
;                 }
.LBB0_453:
	s_and_b32 s48, s47, 1
	s_and_saveexec_b64 s[10:11], s[8:9]
	s_xor_b64 s[10:11], exec, s[10:11]
	s_cbranch_execz .LBB0_466
	s_mul_i32 s30, s48, 0xd000
	v_add_u32_e32 v175, s30, v157
	v_add_u32_e32 v123, s30, v158
	v_mbcnt_lo_u32_b32 v176, -1, 0
	v_mbcnt_hi_u32_b32 v176, -1, v176
	v_bfe_u32 v177, v176, 3, 1
	v_bfe_u32 v176, v176, 2, 1
	v_lshlrev_b32_e32 v177, 7, v177
	v_lshl_add_u32 v176, v176, 2, v177
	v_add3_u32 v178, v169, s30, v176
	v_cndmask_b32_e64 v176, 0, 1.0, s[4:5]
	v_mov_b32_e32 v177, v176
	s_mov_b32 s34, 0x11111111
	s_mov_b32 s35, 0x11111111
	ds_read_b128 v[40:43], v175
	ds_read_b128 v[44:47], v175 offset:16
	ds_read_b128 v[48:51], v175 offset:32
	ds_read_b128 v[52:55], v175 offset:48
	ds_read_b128 v[56:59], v175 offset:64
	ds_read_b128 v[60:63], v123 offset:40960
	v_readfirstlane_b32 s39, v158
	s_nop 3
	s_lshr_b32 s39, s39, 6
	s_cmp_eq_u32 s39, 0
	s_cbranch_scc1 .Lscan_stag_done
.Lscan_stag:
	s_sleep 1
	s_add_i32 s39, s39, -1
	s_cmp_lg_u32 s39, 0
	s_cbranch_scc1 .Lscan_stag
.Lscan_stag_done:
	s_setprio 3
	s_mov_b32 s38, 1
	s_waitcnt lgkmcnt(0)
.Lscan_steps:
	s_waitcnt lgkmcnt(1)
	ds_read_b128 v[72:75], v175 offset:1280
	ds_read_b128 v[76:79], v175 offset:1296
	ds_read_b128 v[80:83], v175 offset:1312
	ds_read_b128 v[84:87], v175 offset:1328
	ds_read_b128 v[88:91], v175 offset:1344
	ds_read_b128 v[92:95], v123 offset:41216
	v_pk_mul_f32 v[106:107], v[64:65], v[44:45] op_sel_hi:[1,0]
	v_pk_mul_f32 v[108:109], v[64:65], v[56:57] op_sel_hi:[1,0]
	v_pk_fma_f32 v[106:107], v[66:67], v[44:45], v[106:107] op_sel:[0,1,0]
	v_pk_fma_f32 v[108:109], v[66:67], v[56:57], v[108:109] op_sel:[0,1,0]
	v_pk_fma_f32 v[106:107], v[68:69], v[46:47], v[106:107] op_sel_hi:[1,0,1]
	v_pk_fma_f32 v[108:109], v[68:69], v[58:59], v[108:109] op_sel_hi:[1,0,1]
	v_pk_fma_f32 v[106:107], v[70:71], v[46:47], v[106:107] op_sel:[0,1,0]
	v_pk_fma_f32 v[108:109], v[70:71], v[58:59], v[108:109] op_sel:[0,1,0]
	v_pk_mul_f32 v[110:111], v[64:65], v[40:41] op_sel_hi:[1,0]
	v_add_f32_dpp v106, v106, v106 quad_perm:[1,0,3,2] row_mask:0xf bank_mask:0xf bound_ctrl:1
	v_add_f32_dpp v107, v107, v107 quad_perm:[1,0,3,2] row_mask:0xf bank_mask:0xf bound_ctrl:1
	v_pk_fma_f32 v[108:109], v[62:63], v[176:177], v[108:109]
	v_pk_mul_f32 v[112:113], v[66:67], v[40:41] op_sel:[0,1]
	v_add_f32_dpp v106, v106, v106 quad_perm:[2,3,0,1] row_mask:0xf bank_mask:0xf bound_ctrl:1
	v_add_f32_dpp v107, v107, v107 quad_perm:[2,3,0,1] row_mask:0xf bank_mask:0xf bound_ctrl:1
	v_add_f32_dpp v148, v108, v108 row_half_mirror row_mask:0xf bank_mask:0xf bound_ctrl:1
	v_add_f32_dpp v148, v109, v109 row_half_mirror row_mask:0xf bank_mask:0xa
	v_add_f32_dpp v106, v106, v106 row_half_mirror row_mask:0xf bank_mask:0xf bound_ctrl:1
	v_add_f32_dpp v107, v107, v107 row_half_mirror row_mask:0xf bank_mask:0xf bound_ctrl:1
	v_pk_mul_f32 v[144:145], v[68:69], v[42:43] op_sel_hi:[1,0]
	v_pk_mul_f32 v[146:147], v[70:71], v[42:43] op_sel:[0,1]
	v_add_f32_dpp v106, v106, v106 row_mirror row_mask:0xf bank_mask:0xf bound_ctrl:1
	v_add_f32_dpp v107, v107, v107 row_mirror row_mask:0xf bank_mask:0xf bound_ctrl:1
	v_pk_fma_f32 v[110:111], v[60:61], v[52:53], v[110:111] op_sel_hi:[1,0,1]
	v_pk_fma_f32 v[112:113], v[60:61], v[52:53], v[112:113] op_sel:[0,1,0]
	v_pk_fma_f32 v[144:145], v[60:61], v[54:55], v[144:145] op_sel_hi:[1,0,1]
	v_pk_fma_f32 v[146:147], v[60:61], v[54:55], v[146:147] op_sel:[0,1,0]
	v_pk_fma_f32 v[64:65], v[106:107], v[48:49], v[110:111] op_sel_hi:[1,0,1]
	v_pk_fma_f32 v[66:67], v[106:107], v[48:49], v[112:113] op_sel:[0,1,0]
	v_pk_fma_f32 v[68:69], v[106:107], v[50:51], v[144:145] op_sel_hi:[1,0,1]
	v_pk_fma_f32 v[70:71], v[106:107], v[50:51], v[146:147] op_sel:[0,1,0]
	s_waitcnt lgkmcnt(0)
	ds_read_b128 v[40:43], v175 offset:2560
	ds_read_b128 v[44:47], v175 offset:2576
	ds_read_b128 v[48:51], v175 offset:2592
	ds_read_b128 v[52:55], v175 offset:2608
	ds_read_b128 v[56:59], v175 offset:2624
	ds_read_b128 v[60:63], v123 offset:41472
	v_pk_mul_f32 v[106:107], v[64:65], v[76:77] op_sel_hi:[1,0]
	v_pk_mul_f32 v[108:109], v[64:65], v[88:89] op_sel_hi:[1,0]
	v_pk_fma_f32 v[106:107], v[66:67], v[76:77], v[106:107] op_sel:[0,1,0]
	v_pk_fma_f32 v[108:109], v[66:67], v[88:89], v[108:109] op_sel:[0,1,0]
	v_pk_fma_f32 v[106:107], v[68:69], v[78:79], v[106:107] op_sel_hi:[1,0,1]
	v_pk_fma_f32 v[108:109], v[68:69], v[90:91], v[108:109] op_sel_hi:[1,0,1]
	v_pk_fma_f32 v[106:107], v[70:71], v[78:79], v[106:107] op_sel:[0,1,0]
	v_pk_fma_f32 v[108:109], v[70:71], v[90:91], v[108:109] op_sel:[0,1,0]
	v_pk_mul_f32 v[110:111], v[64:65], v[72:73] op_sel_hi:[1,0]
	v_add_f32_dpp v106, v106, v106 quad_perm:[1,0,3,2] row_mask:0xf bank_mask:0xf bound_ctrl:1
	v_add_f32_dpp v107, v107, v107 quad_perm:[1,0,3,2] row_mask:0xf bank_mask:0xf bound_ctrl:1
	v_pk_fma_f32 v[108:109], v[94:95], v[176:177], v[108:109]
	v_pk_mul_f32 v[112:113], v[66:67], v[72:73] op_sel:[0,1]
	v_add_f32_dpp v106, v106, v106 quad_perm:[2,3,0,1] row_mask:0xf bank_mask:0xf bound_ctrl:1
	v_add_f32_dpp v107, v107, v107 quad_perm:[2,3,0,1] row_mask:0xf bank_mask:0xf bound_ctrl:1
	v_add_f32_dpp v149, v108, v108 row_half_mirror row_mask:0xf bank_mask:0xf bound_ctrl:1
	v_add_f32_dpp v149, v109, v109 row_half_mirror row_mask:0xf bank_mask:0xa
	v_add_f32_dpp v106, v106, v106 row_half_mirror row_mask:0xf bank_mask:0xf bound_ctrl:1
	v_add_f32_dpp v107, v107, v107 row_half_mirror row_mask:0xf bank_mask:0xf bound_ctrl:1
	v_pk_mul_f32 v[144:145], v[68:69], v[74:75] op_sel_hi:[1,0]
	v_pk_mul_f32 v[146:147], v[70:71], v[74:75] op_sel:[0,1]
	v_add_f32_dpp v150, v148, v148 row_ror:8 row_mask:0xf bank_mask:0xf bound_ctrl:1
	v_add_f32_dpp v150, v149, v149 row_ror:8 row_mask:0xf bank_mask:0xc
	v_add_f32_dpp v106, v106, v106 row_mirror row_mask:0xf bank_mask:0xf bound_ctrl:1
	v_add_f32_dpp v107, v107, v107 row_mirror row_mask:0xf bank_mask:0xf bound_ctrl:1
	v_pk_fma_f32 v[110:111], v[92:93], v[84:85], v[110:111] op_sel_hi:[1,0,1]
	v_pk_fma_f32 v[112:113], v[92:93], v[84:85], v[112:113] op_sel:[0,1,0]
	v_pk_fma_f32 v[144:145], v[92:93], v[86:87], v[144:145] op_sel_hi:[1,0,1]
	v_pk_fma_f32 v[146:147], v[92:93], v[86:87], v[146:147] op_sel:[0,1,0]
	v_add_f32_dpp v150, v150, v150 quad_perm:[1,0,3,2] row_mask:0xf bank_mask:0xf bound_ctrl:1
	v_pk_fma_f32 v[64:65], v[106:107], v[80:81], v[110:111] op_sel_hi:[1,0,1]
	v_pk_fma_f32 v[66:67], v[106:107], v[80:81], v[112:113] op_sel:[0,1,0]
	v_add_f32_dpp v150, v150, v150 quad_perm:[2,3,0,1] row_mask:0xf bank_mask:0xf bound_ctrl:1
	v_pk_fma_f32 v[68:69], v[106:107], v[82:83], v[144:145] op_sel_hi:[1,0,1]
	v_pk_fma_f32 v[70:71], v[106:107], v[82:83], v[146:147] op_sel:[0,1,0]
	s_mov_b64 exec, s[34:35]
	ds_write_b32 v178, v150 offset:0
	s_mov_b64 exec, -1
	s_waitcnt lgkmcnt(1)
; #define SC_GET(X, t) do { const float* p = rec + (t) * 320; w##X = *(const f32x4*)p; a##X = *(const f32x4*)(p + 4); b##X = *(const f32x4*)(p + 8); k##X = *(const f32x4*)(p + 12); q##X = *(const f32x4*)(p + 16); \
;                 v##X = *(const f32x4*)(VVa + (t) * 64); } while (0)
; DI void scan_phase(unsigned char* lds, const Ctx& a, const Op& d, const int variant) {
;     ...
;                 SC_GET(A, 0);
; #pragma unroll 2
;                 for (int t = 0; t < SC_T; t += 2) {
;                     SC_GET(B, t + 1);
;                     SC_STEP(A, t);
;                     if (t + 2 < SC_T) SC_GET(A, t + 2);
;                     SC_STEP(B, t + 1);
;                 }
	ds_read_b128 v[72:75], v175 offset:3840
	ds_read_b128 v[76:79], v175 offset:3856
	ds_read_b128 v[80:83], v175 offset:3872
	ds_read_b128 v[84:87], v175 offset:3888
	ds_read_b128 v[88:91], v175 offset:3904
	ds_read_b128 v[92:95], v123 offset:41728
	v_pk_mul_f32 v[106:107], v[64:65], v[44:45] op_sel_hi:[1,0]
	v_pk_mul_f32 v[108:109], v[64:65], v[56:57] op_sel_hi:[1,0]
	v_pk_fma_f32 v[106:107], v[66:67], v[44:45], v[106:107] op_sel:[0,1,0]
	v_pk_fma_f32 v[108:109], v[66:67], v[56:57], v[108:109] op_sel:[0,1,0]
	v_pk_fma_f32 v[106:107], v[68:69], v[46:47], v[106:107] op_sel_hi:[1,0,1]
	v_pk_fma_f32 v[108:109], v[68:69], v[58:59], v[108:109] op_sel_hi:[1,0,1]
	v_pk_fma_f32 v[106:107], v[70:71], v[46:47], v[106:107] op_sel:[0,1,0]
	v_pk_fma_f32 v[108:109], v[70:71], v[58:59], v[108:109] op_sel:[0,1,0]
	v_pk_mul_f32 v[110:111], v[64:65], v[40:41] op_sel_hi:[1,0]
	v_add_f32_dpp v106, v106, v106 quad_perm:[1,0,3,2] row_mask:0xf bank_mask:0xf bound_ctrl:1
	v_add_f32_dpp v107, v107, v107 quad_perm:[1,0,3,2] row_mask:0xf bank_mask:0xf bound_ctrl:1
	v_pk_fma_f32 v[108:109], v[62:63], v[176:177], v[108:109]
	v_pk_mul_f32 v[112:113], v[66:67], v[40:41] op_sel:[0,1]
	v_add_f32_dpp v106, v106, v106 quad_perm:[2,3,0,1] row_mask:0xf bank_mask:0xf bound_ctrl:1
	v_add_f32_dpp v107, v107, v107 quad_perm:[2,3,0,1] row_mask:0xf bank_mask:0xf bound_ctrl:1
	v_add_f32_dpp v148, v108, v108 row_half_mirror row_mask:0xf bank_mask:0xf bound_ctrl:1
	v_add_f32_dpp v148, v109, v109 row_half_mirror row_mask:0xf bank_mask:0xa
	v_add_f32_dpp v106, v106, v106 row_half_mirror row_mask:0xf bank_mask:0xf bound_ctrl:1
	v_add_f32_dpp v107, v107, v107 row_half_mirror row_mask:0xf bank_mask:0xf bound_ctrl:1
	v_pk_mul_f32 v[144:145], v[68:69], v[42:43] op_sel_hi:[1,0]
	v_pk_mul_f32 v[146:147], v[70:71], v[42:43] op_sel:[0,1]
	v_add_f32_dpp v106, v106, v106 row_mirror row_mask:0xf bank_mask:0xf bound_ctrl:1
	v_add_f32_dpp v107, v107, v107 row_mirror row_mask:0xf bank_mask:0xf bound_ctrl:1
	v_pk_fma_f32 v[110:111], v[60:61], v[52:53], v[110:111] op_sel_hi:[1,0,1]
	v_pk_fma_f32 v[112:113], v[60:61], v[52:53], v[112:113] op_sel:[0,1,0]
	v_pk_fma_f32 v[144:145], v[60:61], v[54:55], v[144:145] op_sel_hi:[1,0,1]
	v_pk_fma_f32 v[146:147], v[60:61], v[54:55], v[146:147] op_sel:[0,1,0]
	v_pk_fma_f32 v[64:65], v[106:107], v[48:49], v[110:111] op_sel_hi:[1,0,1]
	v_pk_fma_f32 v[66:67], v[106:107], v[48:49], v[112:113] op_sel:[0,1,0]
	v_pk_fma_f32 v[68:69], v[106:107], v[50:51], v[144:145] op_sel_hi:[1,0,1]
	v_pk_fma_f32 v[70:71], v[106:107], v[50:51], v[146:147] op_sel:[0,1,0]
	s_waitcnt lgkmcnt(0)
	ds_read_b128 v[40:43], v175 offset:5120
	ds_read_b128 v[44:47], v175 offset:5136
	ds_read_b128 v[48:51], v175 offset:5152
	ds_read_b128 v[52:55], v175 offset:5168
	ds_read_b128 v[56:59], v175 offset:5184
	ds_read_b128 v[60:63], v123 offset:41984
	v_pk_mul_f32 v[106:107], v[64:65], v[76:77] op_sel_hi:[1,0]
	v_pk_mul_f32 v[108:109], v[64:65], v[88:89] op_sel_hi:[1,0]
	v_pk_fma_f32 v[106:107], v[66:67], v[76:77], v[106:107] op_sel:[0,1,0]
	v_pk_fma_f32 v[108:109], v[66:67], v[88:89], v[108:109] op_sel:[0,1,0]
	v_pk_fma_f32 v[106:107], v[68:69], v[78:79], v[106:107] op_sel_hi:[1,0,1]
	v_pk_fma_f32 v[108:109], v[68:69], v[90:91], v[108:109] op_sel_hi:[1,0,1]
	v_pk_fma_f32 v[106:107], v[70:71], v[78:79], v[106:107] op_sel:[0,1,0]
	v_pk_fma_f32 v[108:109], v[70:71], v[90:91], v[108:109] op_sel:[0,1,0]
	v_pk_mul_f32 v[110:111], v[64:65], v[72:73] op_sel_hi:[1,0]
	v_add_f32_dpp v106, v106, v106 quad_perm:[1,0,3,2] row_mask:0xf bank_mask:0xf bound_ctrl:1
	v_add_f32_dpp v107, v107, v107 quad_perm:[1,0,3,2] row_mask:0xf bank_mask:0xf bound_ctrl:1
	v_pk_fma_f32 v[108:109], v[94:95], v[176:177], v[108:109]
	v_pk_mul_f32 v[112:113], v[66:67], v[72:73] op_sel:[0,1]
	v_add_f32_dpp v106, v106, v106 quad_perm:[2,3,0,1] row_mask:0xf bank_mask:0xf bound_ctrl:1
	v_add_f32_dpp v107, v107, v107 quad_perm:[2,3,0,1] row_mask:0xf bank_mask:0xf bound_ctrl:1
	v_add_f32_dpp v149, v108, v108 row_half_mirror row_mask:0xf bank_mask:0xf bound_ctrl:1
	v_add_f32_dpp v149, v109, v109 row_half_mirror row_mask:0xf bank_mask:0xa
	v_add_f32_dpp v106, v106, v106 row_half_mirror row_mask:0xf bank_mask:0xf bound_ctrl:1
	v_add_f32_dpp v107, v107, v107 row_half_mirror row_mask:0xf bank_mask:0xf bound_ctrl:1
	v_pk_mul_f32 v[144:145], v[68:69], v[74:75] op_sel_hi:[1,0]
	v_pk_mul_f32 v[146:147], v[70:71], v[74:75] op_sel:[0,1]
	v_add_f32_dpp v150, v148, v148 row_ror:8 row_mask:0xf bank_mask:0xf bound_ctrl:1
	v_add_f32_dpp v150, v149, v149 row_ror:8 row_mask:0xf bank_mask:0xc
	v_add_f32_dpp v106, v106, v106 row_mirror row_mask:0xf bank_mask:0xf bound_ctrl:1
	v_add_f32_dpp v107, v107, v107 row_mirror row_mask:0xf bank_mask:0xf bound_ctrl:1
	v_pk_fma_f32 v[110:111], v[92:93], v[84:85], v[110:111] op_sel_hi:[1,0,1]
	v_pk_fma_f32 v[112:113], v[92:93], v[84:85], v[112:113] op_sel:[0,1,0]
	v_pk_fma_f32 v[144:145], v[92:93], v[86:87], v[144:145] op_sel_hi:[1,0,1]
	v_pk_fma_f32 v[146:147], v[92:93], v[86:87], v[146:147] op_sel:[0,1,0]
	v_add_f32_dpp v150, v150, v150 quad_perm:[1,0,3,2] row_mask:0xf bank_mask:0xf bound_ctrl:1
	v_pk_fma_f32 v[64:65], v[106:107], v[80:81], v[110:111] op_sel_hi:[1,0,1]
	v_pk_fma_f32 v[66:67], v[106:107], v[80:81], v[112:113] op_sel:[0,1,0]
	v_add_f32_dpp v150, v150, v150 quad_perm:[2,3,0,1] row_mask:0xf bank_mask:0xf bound_ctrl:1
	v_pk_fma_f32 v[68:69], v[106:107], v[82:83], v[144:145] op_sel_hi:[1,0,1]
	v_pk_fma_f32 v[70:71], v[106:107], v[82:83], v[146:147] op_sel:[0,1,0]
	s_mov_b64 exec, s[34:35]
	ds_write_b32 v178, v150 offset:256
	s_mov_b64 exec, -1
	s_waitcnt lgkmcnt(1)
; #define SC_GET(X, t) do { const float* p = rec + (t) * 320; w##X = *(const f32x4*)p; a##X = *(const f32x4*)(p + 4); b##X = *(const f32x4*)(p + 8); k##X = *(const f32x4*)(p + 12); q##X = *(const f32x4*)(p + 16); \
;                 v##X = *(const f32x4*)(VVa + (t) * 64); } while (0)
; DI void scan_phase(unsigned char* lds, const Ctx& a, const Op& d, const int variant) {
;     ...
;                 SC_GET(A, 0);
; #pragma unroll 2
;                 for (int t = 0; t < SC_T; t += 2) {
;                     SC_GET(B, t + 1);
;                     SC_STEP(A, t);
;                     if (t + 2 < SC_T) SC_GET(A, t + 2);
;                     SC_STEP(B, t + 1);
;                 }
	ds_read_b128 v[72:75], v175 offset:6400
	ds_read_b128 v[76:79], v175 offset:6416
	ds_read_b128 v[80:83], v175 offset:6432
	ds_read_b128 v[84:87], v175 offset:6448
	ds_read_b128 v[88:91], v175 offset:6464
	ds_read_b128 v[92:95], v123 offset:42240
	v_pk_mul_f32 v[106:107], v[64:65], v[44:45] op_sel_hi:[1,0]
	v_pk_mul_f32 v[108:109], v[64:65], v[56:57] op_sel_hi:[1,0]
	v_pk_fma_f32 v[106:107], v[66:67], v[44:45], v[106:107] op_sel:[0,1,0]
	v_pk_fma_f32 v[108:109], v[66:67], v[56:57], v[108:109] op_sel:[0,1,0]
	v_pk_fma_f32 v[106:107], v[68:69], v[46:47], v[106:107] op_sel_hi:[1,0,1]
	v_pk_fma_f32 v[108:109], v[68:69], v[58:59], v[108:109] op_sel_hi:[1,0,1]
	v_pk_fma_f32 v[106:107], v[70:71], v[46:47], v[106:107] op_sel:[0,1,0]
	v_pk_fma_f32 v[108:109], v[70:71], v[58:59], v[108:109] op_sel:[0,1,0]
	v_pk_mul_f32 v[110:111], v[64:65], v[40:41] op_sel_hi:[1,0]
	v_add_f32_dpp v106, v106, v106 quad_perm:[1,0,3,2] row_mask:0xf bank_mask:0xf bound_ctrl:1
	v_add_f32_dpp v107, v107, v107 quad_perm:[1,0,3,2] row_mask:0xf bank_mask:0xf bound_ctrl:1
	v_pk_fma_f32 v[108:109], v[62:63], v[176:177], v[108:109]
	v_pk_mul_f32 v[112:113], v[66:67], v[40:41] op_sel:[0,1]
	v_add_f32_dpp v106, v106, v106 quad_perm:[2,3,0,1] row_mask:0xf bank_mask:0xf bound_ctrl:1
	v_add_f32_dpp v107, v107, v107 quad_perm:[2,3,0,1] row_mask:0xf bank_mask:0xf bound_ctrl:1
	v_add_f32_dpp v148, v108, v108 row_half_mirror row_mask:0xf bank_mask:0xf bound_ctrl:1
	v_add_f32_dpp v148, v109, v109 row_half_mirror row_mask:0xf bank_mask:0xa
	v_add_f32_dpp v106, v106, v106 row_half_mirror row_mask:0xf bank_mask:0xf bound_ctrl:1
	v_add_f32_dpp v107, v107, v107 row_half_mirror row_mask:0xf bank_mask:0xf bound_ctrl:1
	v_pk_mul_f32 v[144:145], v[68:69], v[42:43] op_sel_hi:[1,0]
	v_pk_mul_f32 v[146:147], v[70:71], v[42:43] op_sel:[0,1]
	v_add_f32_dpp v106, v106, v106 row_mirror row_mask:0xf bank_mask:0xf bound_ctrl:1
	v_add_f32_dpp v107, v107, v107 row_mirror row_mask:0xf bank_mask:0xf bound_ctrl:1
	v_pk_fma_f32 v[110:111], v[60:61], v[52:53], v[110:111] op_sel_hi:[1,0,1]
	v_pk_fma_f32 v[112:113], v[60:61], v[52:53], v[112:113] op_sel:[0,1,0]
	v_pk_fma_f32 v[144:145], v[60:61], v[54:55], v[144:145] op_sel_hi:[1,0,1]
	v_pk_fma_f32 v[146:147], v[60:61], v[54:55], v[146:147] op_sel:[0,1,0]
	v_pk_fma_f32 v[64:65], v[106:107], v[48:49], v[110:111] op_sel_hi:[1,0,1]
	v_pk_fma_f32 v[66:67], v[106:107], v[48:49], v[112:113] op_sel:[0,1,0]
	v_pk_fma_f32 v[68:69], v[106:107], v[50:51], v[144:145] op_sel_hi:[1,0,1]
	v_pk_fma_f32 v[70:71], v[106:107], v[50:51], v[146:147] op_sel:[0,1,0]
	s_waitcnt lgkmcnt(0)
	ds_read_b128 v[40:43], v175 offset:7680
	ds_read_b128 v[44:47], v175 offset:7696
	ds_read_b128 v[48:51], v175 offset:7712
	ds_read_b128 v[52:55], v175 offset:7728
	ds_read_b128 v[56:59], v175 offset:7744
	ds_read_b128 v[60:63], v123 offset:42496
	v_pk_mul_f32 v[106:107], v[64:65], v[76:77] op_sel_hi:[1,0]
	v_pk_mul_f32 v[108:109], v[64:65], v[88:89] op_sel_hi:[1,0]
	v_pk_fma_f32 v[106:107], v[66:67], v[76:77], v[106:107] op_sel:[0,1,0]
	v_pk_fma_f32 v[108:109], v[66:67], v[88:89], v[108:109] op_sel:[0,1,0]
	v_pk_fma_f32 v[106:107], v[68:69], v[78:79], v[106:107] op_sel_hi:[1,0,1]
	v_pk_fma_f32 v[108:109], v[68:69], v[90:91], v[108:109] op_sel_hi:[1,0,1]
	v_pk_fma_f32 v[106:107], v[70:71], v[78:79], v[106:107] op_sel:[0,1,0]
	v_pk_fma_f32 v[108:109], v[70:71], v[90:91], v[108:109] op_sel:[0,1,0]
	v_pk_mul_f32 v[110:111], v[64:65], v[72:73] op_sel_hi:[1,0]
	v_add_f32_dpp v106, v106, v106 quad_perm:[1,0,3,2] row_mask:0xf bank_mask:0xf bound_ctrl:1
	v_add_f32_dpp v107, v107, v107 quad_perm:[1,0,3,2] row_mask:0xf bank_mask:0xf bound_ctrl:1
	v_pk_fma_f32 v[108:109], v[94:95], v[176:177], v[108:109]
	v_pk_mul_f32 v[112:113], v[66:67], v[72:73] op_sel:[0,1]
	v_add_f32_dpp v106, v106, v106 quad_perm:[2,3,0,1] row_mask:0xf bank_mask:0xf bound_ctrl:1
	v_add_f32_dpp v107, v107, v107 quad_perm:[2,3,0,1] row_mask:0xf bank_mask:0xf bound_ctrl:1
	v_add_f32_dpp v149, v108, v108 row_half_mirror row_mask:0xf bank_mask:0xf bound_ctrl:1
	v_add_f32_dpp v149, v109, v109 row_half_mirror row_mask:0xf bank_mask:0xa
	v_add_f32_dpp v106, v106, v106 row_half_mirror row_mask:0xf bank_mask:0xf bound_ctrl:1
	v_add_f32_dpp v107, v107, v107 row_half_mirror row_mask:0xf bank_mask:0xf bound_ctrl:1
	v_pk_mul_f32 v[144:145], v[68:69], v[74:75] op_sel_hi:[1,0]
	v_pk_mul_f32 v[146:147], v[70:71], v[74:75] op_sel:[0,1]
	v_add_f32_dpp v150, v148, v148 row_ror:8 row_mask:0xf bank_mask:0xf bound_ctrl:1
	v_add_f32_dpp v150, v149, v149 row_ror:8 row_mask:0xf bank_mask:0xc
	v_add_f32_dpp v106, v106, v106 row_mirror row_mask:0xf bank_mask:0xf bound_ctrl:1
	v_add_f32_dpp v107, v107, v107 row_mirror row_mask:0xf bank_mask:0xf bound_ctrl:1
	v_pk_fma_f32 v[110:111], v[92:93], v[84:85], v[110:111] op_sel_hi:[1,0,1]
	v_pk_fma_f32 v[112:113], v[92:93], v[84:85], v[112:113] op_sel:[0,1,0]
	v_pk_fma_f32 v[144:145], v[92:93], v[86:87], v[144:145] op_sel_hi:[1,0,1]
	v_pk_fma_f32 v[146:147], v[92:93], v[86:87], v[146:147] op_sel:[0,1,0]
	v_add_f32_dpp v150, v150, v150 quad_perm:[1,0,3,2] row_mask:0xf bank_mask:0xf bound_ctrl:1
	v_pk_fma_f32 v[64:65], v[106:107], v[80:81], v[110:111] op_sel_hi:[1,0,1]
	v_pk_fma_f32 v[66:67], v[106:107], v[80:81], v[112:113] op_sel:[0,1,0]
	v_add_f32_dpp v150, v150, v150 quad_perm:[2,3,0,1] row_mask:0xf bank_mask:0xf bound_ctrl:1
	v_pk_fma_f32 v[68:69], v[106:107], v[82:83], v[144:145] op_sel_hi:[1,0,1]
	v_pk_fma_f32 v[70:71], v[106:107], v[82:83], v[146:147] op_sel:[0,1,0]
	s_mov_b64 exec, s[34:35]
	ds_write_b32 v178, v150 offset:512
	s_mov_b64 exec, -1
	s_waitcnt lgkmcnt(1)
; #define SC_GET(X, t) do { const float* p = rec + (t) * 320; w##X = *(const f32x4*)p; a##X = *(const f32x4*)(p + 4); b##X = *(const f32x4*)(p + 8); k##X = *(const f32x4*)(p + 12); q##X = *(const f32x4*)(p + 16); \
;                 v##X = *(const f32x4*)(VVa + (t) * 64); } while (0)
; DI void scan_phase(unsigned char* lds, const Ctx& a, const Op& d, const int variant) {
;     ...
;                 SC_GET(A, 0);
; #pragma unroll 2
;                 for (int t = 0; t < SC_T; t += 2) {
;                     SC_GET(B, t + 1);
;                     SC_STEP(A, t);
;                     if (t + 2 < SC_T) SC_GET(A, t + 2);
;                     SC_STEP(B, t + 1);
;                 }
	ds_read_b128 v[72:75], v175 offset:8960
	ds_read_b128 v[76:79], v175 offset:8976
	ds_read_b128 v[80:83], v175 offset:8992
	ds_read_b128 v[84:87], v175 offset:9008
	ds_read_b128 v[88:91], v175 offset:9024
	ds_read_b128 v[92:95], v123 offset:42752
	v_pk_mul_f32 v[106:107], v[64:65], v[44:45] op_sel_hi:[1,0]
	v_pk_mul_f32 v[108:109], v[64:65], v[56:57] op_sel_hi:[1,0]
	v_pk_fma_f32 v[106:107], v[66:67], v[44:45], v[106:107] op_sel:[0,1,0]
	v_pk_fma_f32 v[108:109], v[66:67], v[56:57], v[108:109] op_sel:[0,1,0]
	v_pk_fma_f32 v[106:107], v[68:69], v[46:47], v[106:107] op_sel_hi:[1,0,1]
	v_pk_fma_f32 v[108:109], v[68:69], v[58:59], v[108:109] op_sel_hi:[1,0,1]
	v_pk_fma_f32 v[106:107], v[70:71], v[46:47], v[106:107] op_sel:[0,1,0]
	v_pk_fma_f32 v[108:109], v[70:71], v[58:59], v[108:109] op_sel:[0,1,0]
	v_pk_mul_f32 v[110:111], v[64:65], v[40:41] op_sel_hi:[1,0]
	v_add_f32_dpp v106, v106, v106 quad_perm:[1,0,3,2] row_mask:0xf bank_mask:0xf bound_ctrl:1
	v_add_f32_dpp v107, v107, v107 quad_perm:[1,0,3,2] row_mask:0xf bank_mask:0xf bound_ctrl:1
	v_pk_fma_f32 v[108:109], v[62:63], v[176:177], v[108:109]
	v_pk_mul_f32 v[112:113], v[66:67], v[40:41] op_sel:[0,1]
	v_add_f32_dpp v106, v106, v106 quad_perm:[2,3,0,1] row_mask:0xf bank_mask:0xf bound_ctrl:1
	v_add_f32_dpp v107, v107, v107 quad_perm:[2,3,0,1] row_mask:0xf bank_mask:0xf bound_ctrl:1
	v_add_f32_dpp v148, v108, v108 row_half_mirror row_mask:0xf bank_mask:0xf bound_ctrl:1
	v_add_f32_dpp v148, v109, v109 row_half_mirror row_mask:0xf bank_mask:0xa
	v_add_f32_dpp v106, v106, v106 row_half_mirror row_mask:0xf bank_mask:0xf bound_ctrl:1
	v_add_f32_dpp v107, v107, v107 row_half_mirror row_mask:0xf bank_mask:0xf bound_ctrl:1
	v_pk_mul_f32 v[144:145], v[68:69], v[42:43] op_sel_hi:[1,0]
	v_pk_mul_f32 v[146:147], v[70:71], v[42:43] op_sel:[0,1]
	v_add_f32_dpp v106, v106, v106 row_mirror row_mask:0xf bank_mask:0xf bound_ctrl:1
	v_add_f32_dpp v107, v107, v107 row_mirror row_mask:0xf bank_mask:0xf bound_ctrl:1
	v_pk_fma_f32 v[110:111], v[60:61], v[52:53], v[110:111] op_sel_hi:[1,0,1]
	v_pk_fma_f32 v[112:113], v[60:61], v[52:53], v[112:113] op_sel:[0,1,0]
	v_pk_fma_f32 v[144:145], v[60:61], v[54:55], v[144:145] op_sel_hi:[1,0,1]
	v_pk_fma_f32 v[146:147], v[60:61], v[54:55], v[146:147] op_sel:[0,1,0]
	v_pk_fma_f32 v[64:65], v[106:107], v[48:49], v[110:111] op_sel_hi:[1,0,1]
	v_pk_fma_f32 v[66:67], v[106:107], v[48:49], v[112:113] op_sel:[0,1,0]
	v_pk_fma_f32 v[68:69], v[106:107], v[50:51], v[144:145] op_sel_hi:[1,0,1]
	v_pk_fma_f32 v[70:71], v[106:107], v[50:51], v[146:147] op_sel:[0,1,0]
	s_waitcnt lgkmcnt(0)
	ds_read_b128 v[40:43], v175 offset:10240
	ds_read_b128 v[44:47], v175 offset:10256
	ds_read_b128 v[48:51], v175 offset:10272
	ds_read_b128 v[52:55], v175 offset:10288
	ds_read_b128 v[56:59], v175 offset:10304
	ds_read_b128 v[60:63], v123 offset:43008
	v_pk_mul_f32 v[106:107], v[64:65], v[76:77] op_sel_hi:[1,0]
	v_pk_mul_f32 v[108:109], v[64:65], v[88:89] op_sel_hi:[1,0]
	v_pk_fma_f32 v[106:107], v[66:67], v[76:77], v[106:107] op_sel:[0,1,0]
	v_pk_fma_f32 v[108:109], v[66:67], v[88:89], v[108:109] op_sel:[0,1,0]
	v_pk_fma_f32 v[106:107], v[68:69], v[78:79], v[106:107] op_sel_hi:[1,0,1]
	v_pk_fma_f32 v[108:109], v[68:69], v[90:91], v[108:109] op_sel_hi:[1,0,1]
	v_pk_fma_f32 v[106:107], v[70:71], v[78:79], v[106:107] op_sel:[0,1,0]
	v_pk_fma_f32 v[108:109], v[70:71], v[90:91], v[108:109] op_sel:[0,1,0]
	v_pk_mul_f32 v[110:111], v[64:65], v[72:73] op_sel_hi:[1,0]
	v_add_f32_dpp v106, v106, v106 quad_perm:[1,0,3,2] row_mask:0xf bank_mask:0xf bound_ctrl:1
	v_add_f32_dpp v107, v107, v107 quad_perm:[1,0,3,2] row_mask:0xf bank_mask:0xf bound_ctrl:1
	v_pk_fma_f32 v[108:109], v[94:95], v[176:177], v[108:109]
	v_pk_mul_f32 v[112:113], v[66:67], v[72:73] op_sel:[0,1]
	v_add_f32_dpp v106, v106, v106 quad_perm:[2,3,0,1] row_mask:0xf bank_mask:0xf bound_ctrl:1
	v_add_f32_dpp v107, v107, v107 quad_perm:[2,3,0,1] row_mask:0xf bank_mask:0xf bound_ctrl:1
	v_add_f32_dpp v149, v108, v108 row_half_mirror row_mask:0xf bank_mask:0xf bound_ctrl:1
	v_add_f32_dpp v149, v109, v109 row_half_mirror row_mask:0xf bank_mask:0xa
	v_add_f32_dpp v106, v106, v106 row_half_mirror row_mask:0xf bank_mask:0xf bound_ctrl:1
	v_add_f32_dpp v107, v107, v107 row_half_mirror row_mask:0xf bank_mask:0xf bound_ctrl:1
	v_pk_mul_f32 v[144:145], v[68:69], v[74:75] op_sel_hi:[1,0]
	v_pk_mul_f32 v[146:147], v[70:71], v[74:75] op_sel:[0,1]
	v_add_f32_dpp v150, v148, v148 row_ror:8 row_mask:0xf bank_mask:0xf bound_ctrl:1
	v_add_f32_dpp v150, v149, v149 row_ror:8 row_mask:0xf bank_mask:0xc
	v_add_f32_dpp v106, v106, v106 row_mirror row_mask:0xf bank_mask:0xf bound_ctrl:1
	v_add_f32_dpp v107, v107, v107 row_mirror row_mask:0xf bank_mask:0xf bound_ctrl:1
	v_pk_fma_f32 v[110:111], v[92:93], v[84:85], v[110:111] op_sel_hi:[1,0,1]
	v_pk_fma_f32 v[112:113], v[92:93], v[84:85], v[112:113] op_sel:[0,1,0]
	v_pk_fma_f32 v[144:145], v[92:93], v[86:87], v[144:145] op_sel_hi:[1,0,1]
	v_pk_fma_f32 v[146:147], v[92:93], v[86:87], v[146:147] op_sel:[0,1,0]
	v_add_f32_dpp v150, v150, v150 quad_perm:[1,0,3,2] row_mask:0xf bank_mask:0xf bound_ctrl:1
	v_pk_fma_f32 v[64:65], v[106:107], v[80:81], v[110:111] op_sel_hi:[1,0,1]
	v_pk_fma_f32 v[66:67], v[106:107], v[80:81], v[112:113] op_sel:[0,1,0]
	v_add_f32_dpp v150, v150, v150 quad_perm:[2,3,0,1] row_mask:0xf bank_mask:0xf bound_ctrl:1
	v_pk_fma_f32 v[68:69], v[106:107], v[82:83], v[144:145] op_sel_hi:[1,0,1]
	v_pk_fma_f32 v[70:71], v[106:107], v[82:83], v[146:147] op_sel:[0,1,0]
	s_mov_b64 exec, s[34:35]
	ds_write_b32 v178, v150 offset:768
	s_mov_b64 exec, -1
	s_waitcnt lgkmcnt(1)
; #define SC_GET(X, t) do { const float* p = rec + (t) * 320; w##X = *(const f32x4*)p; a##X = *(const f32x4*)(p + 4); b##X = *(const f32x4*)(p + 8); k##X = *(const f32x4*)(p + 12); q##X = *(const f32x4*)(p + 16); \
;                 v##X = *(const f32x4*)(VVa + (t) * 64); } while (0)
; DI void scan_phase(unsigned char* lds, const Ctx& a, const Op& d, const int variant) {
;     ...
;                 SC_GET(A, 0);
; #pragma unroll 2
;                 for (int t = 0; t < SC_T; t += 2) {
;                     SC_GET(B, t + 1);
;                     SC_STEP(A, t);
;                     if (t + 2 < SC_T) SC_GET(A, t + 2);
;                     SC_STEP(B, t + 1);
;                 }
	ds_read_b128 v[72:75], v175 offset:11520
	ds_read_b128 v[76:79], v175 offset:11536
	ds_read_b128 v[80:83], v175 offset:11552
	ds_read_b128 v[84:87], v175 offset:11568
	ds_read_b128 v[88:91], v175 offset:11584
	ds_read_b128 v[92:95], v123 offset:43264
	v_pk_mul_f32 v[106:107], v[64:65], v[44:45] op_sel_hi:[1,0]
	v_pk_mul_f32 v[108:109], v[64:65], v[56:57] op_sel_hi:[1,0]
	v_pk_fma_f32 v[106:107], v[66:67], v[44:45], v[106:107] op_sel:[0,1,0]
	v_pk_fma_f32 v[108:109], v[66:67], v[56:57], v[108:109] op_sel:[0,1,0]
	v_pk_fma_f32 v[106:107], v[68:69], v[46:47], v[106:107] op_sel_hi:[1,0,1]
	v_pk_fma_f32 v[108:109], v[68:69], v[58:59], v[108:109] op_sel_hi:[1,0,1]
	v_pk_fma_f32 v[106:107], v[70:71], v[46:47], v[106:107] op_sel:[0,1,0]
	v_pk_fma_f32 v[108:109], v[70:71], v[58:59], v[108:109] op_sel:[0,1,0]
	v_pk_mul_f32 v[110:111], v[64:65], v[40:41] op_sel_hi:[1,0]
	v_add_f32_dpp v106, v106, v106 quad_perm:[1,0,3,2] row_mask:0xf bank_mask:0xf bound_ctrl:1
	v_add_f32_dpp v107, v107, v107 quad_perm:[1,0,3,2] row_mask:0xf bank_mask:0xf bound_ctrl:1
	v_pk_fma_f32 v[108:109], v[62:63], v[176:177], v[108:109]
	v_pk_mul_f32 v[112:113], v[66:67], v[40:41] op_sel:[0,1]
	v_add_f32_dpp v106, v106, v106 quad_perm:[2,3,0,1] row_mask:0xf bank_mask:0xf bound_ctrl:1
	v_add_f32_dpp v107, v107, v107 quad_perm:[2,3,0,1] row_mask:0xf bank_mask:0xf bound_ctrl:1
	v_add_f32_dpp v148, v108, v108 row_half_mirror row_mask:0xf bank_mask:0xf bound_ctrl:1
	v_add_f32_dpp v148, v109, v109 row_half_mirror row_mask:0xf bank_mask:0xa
	v_add_f32_dpp v106, v106, v106 row_half_mirror row_mask:0xf bank_mask:0xf bound_ctrl:1
	v_add_f32_dpp v107, v107, v107 row_half_mirror row_mask:0xf bank_mask:0xf bound_ctrl:1
	v_pk_mul_f32 v[144:145], v[68:69], v[42:43] op_sel_hi:[1,0]
	v_pk_mul_f32 v[146:147], v[70:71], v[42:43] op_sel:[0,1]
	v_add_f32_dpp v106, v106, v106 row_mirror row_mask:0xf bank_mask:0xf bound_ctrl:1
	v_add_f32_dpp v107, v107, v107 row_mirror row_mask:0xf bank_mask:0xf bound_ctrl:1
	v_pk_fma_f32 v[110:111], v[60:61], v[52:53], v[110:111] op_sel_hi:[1,0,1]
	v_pk_fma_f32 v[112:113], v[60:61], v[52:53], v[112:113] op_sel:[0,1,0]
	v_pk_fma_f32 v[144:145], v[60:61], v[54:55], v[144:145] op_sel_hi:[1,0,1]
	v_pk_fma_f32 v[146:147], v[60:61], v[54:55], v[146:147] op_sel:[0,1,0]
	v_pk_fma_f32 v[64:65], v[106:107], v[48:49], v[110:111] op_sel_hi:[1,0,1]
	v_pk_fma_f32 v[66:67], v[106:107], v[48:49], v[112:113] op_sel:[0,1,0]
	v_pk_fma_f32 v[68:69], v[106:107], v[50:51], v[144:145] op_sel_hi:[1,0,1]
	v_pk_fma_f32 v[70:71], v[106:107], v[50:51], v[146:147] op_sel:[0,1,0]
	s_waitcnt lgkmcnt(0)
	ds_read_b128 v[40:43], v175 offset:12800
	ds_read_b128 v[44:47], v175 offset:12816
	ds_read_b128 v[48:51], v175 offset:12832
	ds_read_b128 v[52:55], v175 offset:12848
	ds_read_b128 v[56:59], v175 offset:12864
	ds_read_b128 v[60:63], v123 offset:43520
	v_pk_mul_f32 v[106:107], v[64:65], v[76:77] op_sel_hi:[1,0]
	v_pk_mul_f32 v[108:109], v[64:65], v[88:89] op_sel_hi:[1,0]
	v_pk_fma_f32 v[106:107], v[66:67], v[76:77], v[106:107] op_sel:[0,1,0]
	v_pk_fma_f32 v[108:109], v[66:67], v[88:89], v[108:109] op_sel:[0,1,0]
	v_pk_fma_f32 v[106:107], v[68:69], v[78:79], v[106:107] op_sel_hi:[1,0,1]
	v_pk_fma_f32 v[108:109], v[68:69], v[90:91], v[108:109] op_sel_hi:[1,0,1]
	v_pk_fma_f32 v[106:107], v[70:71], v[78:79], v[106:107] op_sel:[0,1,0]
	v_pk_fma_f32 v[108:109], v[70:71], v[90:91], v[108:109] op_sel:[0,1,0]
	v_pk_mul_f32 v[110:111], v[64:65], v[72:73] op_sel_hi:[1,0]
	v_add_f32_dpp v106, v106, v106 quad_perm:[1,0,3,2] row_mask:0xf bank_mask:0xf bound_ctrl:1
	v_add_f32_dpp v107, v107, v107 quad_perm:[1,0,3,2] row_mask:0xf bank_mask:0xf bound_ctrl:1
	v_pk_fma_f32 v[108:109], v[94:95], v[176:177], v[108:109]
	v_pk_mul_f32 v[112:113], v[66:67], v[72:73] op_sel:[0,1]
	v_add_f32_dpp v106, v106, v106 quad_perm:[2,3,0,1] row_mask:0xf bank_mask:0xf bound_ctrl:1
	v_add_f32_dpp v107, v107, v107 quad_perm:[2,3,0,1] row_mask:0xf bank_mask:0xf bound_ctrl:1
	v_add_f32_dpp v149, v108, v108 row_half_mirror row_mask:0xf bank_mask:0xf bound_ctrl:1
	v_add_f32_dpp v149, v109, v109 row_half_mirror row_mask:0xf bank_mask:0xa
	v_add_f32_dpp v106, v106, v106 row_half_mirror row_mask:0xf bank_mask:0xf bound_ctrl:1
	v_add_f32_dpp v107, v107, v107 row_half_mirror row_mask:0xf bank_mask:0xf bound_ctrl:1
	v_pk_mul_f32 v[144:145], v[68:69], v[74:75] op_sel_hi:[1,0]
	v_pk_mul_f32 v[146:147], v[70:71], v[74:75] op_sel:[0,1]
	v_add_f32_dpp v150, v148, v148 row_ror:8 row_mask:0xf bank_mask:0xf bound_ctrl:1
	v_add_f32_dpp v150, v149, v149 row_ror:8 row_mask:0xf bank_mask:0xc
	v_add_f32_dpp v106, v106, v106 row_mirror row_mask:0xf bank_mask:0xf bound_ctrl:1
	v_add_f32_dpp v107, v107, v107 row_mirror row_mask:0xf bank_mask:0xf bound_ctrl:1
	v_pk_fma_f32 v[110:111], v[92:93], v[84:85], v[110:111] op_sel_hi:[1,0,1]
	v_pk_fma_f32 v[112:113], v[92:93], v[84:85], v[112:113] op_sel:[0,1,0]
	v_pk_fma_f32 v[144:145], v[92:93], v[86:87], v[144:145] op_sel_hi:[1,0,1]
	v_pk_fma_f32 v[146:147], v[92:93], v[86:87], v[146:147] op_sel:[0,1,0]
	v_add_f32_dpp v150, v150, v150 quad_perm:[1,0,3,2] row_mask:0xf bank_mask:0xf bound_ctrl:1
	v_pk_fma_f32 v[64:65], v[106:107], v[80:81], v[110:111] op_sel_hi:[1,0,1]
	v_pk_fma_f32 v[66:67], v[106:107], v[80:81], v[112:113] op_sel:[0,1,0]
	v_add_f32_dpp v150, v150, v150 quad_perm:[2,3,0,1] row_mask:0xf bank_mask:0xf bound_ctrl:1
	v_pk_fma_f32 v[68:69], v[106:107], v[82:83], v[144:145] op_sel_hi:[1,0,1]
	v_pk_fma_f32 v[70:71], v[106:107], v[82:83], v[146:147] op_sel:[0,1,0]
	s_mov_b64 exec, s[34:35]
	ds_write_b32 v178, v150 offset:1024
	s_mov_b64 exec, -1
	s_waitcnt lgkmcnt(1)
; #define SC_GET(X, t) do { const float* p = rec + (t) * 320; w##X = *(const f32x4*)p; a##X = *(const f32x4*)(p + 4); b##X = *(const f32x4*)(p + 8); k##X = *(const f32x4*)(p + 12); q##X = *(const f32x4*)(p + 16); \
;                 v##X = *(const f32x4*)(VVa + (t) * 64); } while (0)
; DI void scan_phase(unsigned char* lds, const Ctx& a, const Op& d, const int variant) {
;     ...
;                 SC_GET(A, 0);
; #pragma unroll 2
;                 for (int t = 0; t < SC_T; t += 2) {
;                     SC_GET(B, t + 1);
;                     SC_STEP(A, t);
;                     if (t + 2 < SC_T) SC_GET(A, t + 2);
;                     SC_STEP(B, t + 1);
;                 }
	ds_read_b128 v[72:75], v175 offset:14080
	ds_read_b128 v[76:79], v175 offset:14096
	ds_read_b128 v[80:83], v175 offset:14112
	ds_read_b128 v[84:87], v175 offset:14128
	ds_read_b128 v[88:91], v175 offset:14144
	ds_read_b128 v[92:95], v123 offset:43776
	v_pk_mul_f32 v[106:107], v[64:65], v[44:45] op_sel_hi:[1,0]
	v_pk_mul_f32 v[108:109], v[64:65], v[56:57] op_sel_hi:[1,0]
	v_pk_fma_f32 v[106:107], v[66:67], v[44:45], v[106:107] op_sel:[0,1,0]
	v_pk_fma_f32 v[108:109], v[66:67], v[56:57], v[108:109] op_sel:[0,1,0]
	v_pk_fma_f32 v[106:107], v[68:69], v[46:47], v[106:107] op_sel_hi:[1,0,1]
	v_pk_fma_f32 v[108:109], v[68:69], v[58:59], v[108:109] op_sel_hi:[1,0,1]
	v_pk_fma_f32 v[106:107], v[70:71], v[46:47], v[106:107] op_sel:[0,1,0]
	v_pk_fma_f32 v[108:109], v[70:71], v[58:59], v[108:109] op_sel:[0,1,0]
	v_pk_mul_f32 v[110:111], v[64:65], v[40:41] op_sel_hi:[1,0]
	v_add_f32_dpp v106, v106, v106 quad_perm:[1,0,3,2] row_mask:0xf bank_mask:0xf bound_ctrl:1
	v_add_f32_dpp v107, v107, v107 quad_perm:[1,0,3,2] row_mask:0xf bank_mask:0xf bound_ctrl:1
	v_pk_fma_f32 v[108:109], v[62:63], v[176:177], v[108:109]
	v_pk_mul_f32 v[112:113], v[66:67], v[40:41] op_sel:[0,1]
	v_add_f32_dpp v106, v106, v106 quad_perm:[2,3,0,1] row_mask:0xf bank_mask:0xf bound_ctrl:1
	v_add_f32_dpp v107, v107, v107 quad_perm:[2,3,0,1] row_mask:0xf bank_mask:0xf bound_ctrl:1
	v_add_f32_dpp v148, v108, v108 row_half_mirror row_mask:0xf bank_mask:0xf bound_ctrl:1
	v_add_f32_dpp v148, v109, v109 row_half_mirror row_mask:0xf bank_mask:0xa
	v_add_f32_dpp v106, v106, v106 row_half_mirror row_mask:0xf bank_mask:0xf bound_ctrl:1
	v_add_f32_dpp v107, v107, v107 row_half_mirror row_mask:0xf bank_mask:0xf bound_ctrl:1
	v_pk_mul_f32 v[144:145], v[68:69], v[42:43] op_sel_hi:[1,0]
	v_pk_mul_f32 v[146:147], v[70:71], v[42:43] op_sel:[0,1]
	v_add_f32_dpp v106, v106, v106 row_mirror row_mask:0xf bank_mask:0xf bound_ctrl:1
	v_add_f32_dpp v107, v107, v107 row_mirror row_mask:0xf bank_mask:0xf bound_ctrl:1
	v_pk_fma_f32 v[110:111], v[60:61], v[52:53], v[110:111] op_sel_hi:[1,0,1]
	v_pk_fma_f32 v[112:113], v[60:61], v[52:53], v[112:113] op_sel:[0,1,0]
	v_pk_fma_f32 v[144:145], v[60:61], v[54:55], v[144:145] op_sel_hi:[1,0,1]
	v_pk_fma_f32 v[146:147], v[60:61], v[54:55], v[146:147] op_sel:[0,1,0]
	v_pk_fma_f32 v[64:65], v[106:107], v[48:49], v[110:111] op_sel_hi:[1,0,1]
	v_pk_fma_f32 v[66:67], v[106:107], v[48:49], v[112:113] op_sel:[0,1,0]
	v_pk_fma_f32 v[68:69], v[106:107], v[50:51], v[144:145] op_sel_hi:[1,0,1]
	v_pk_fma_f32 v[70:71], v[106:107], v[50:51], v[146:147] op_sel:[0,1,0]
	s_waitcnt lgkmcnt(0)
	ds_read_b128 v[40:43], v175 offset:15360
	ds_read_b128 v[44:47], v175 offset:15376
	ds_read_b128 v[48:51], v175 offset:15392
	ds_read_b128 v[52:55], v175 offset:15408
	ds_read_b128 v[56:59], v175 offset:15424
	ds_read_b128 v[60:63], v123 offset:44032
	v_pk_mul_f32 v[106:107], v[64:65], v[76:77] op_sel_hi:[1,0]
	v_pk_mul_f32 v[108:109], v[64:65], v[88:89] op_sel_hi:[1,0]
	v_pk_fma_f32 v[106:107], v[66:67], v[76:77], v[106:107] op_sel:[0,1,0]
	v_pk_fma_f32 v[108:109], v[66:67], v[88:89], v[108:109] op_sel:[0,1,0]
	v_pk_fma_f32 v[106:107], v[68:69], v[78:79], v[106:107] op_sel_hi:[1,0,1]
	v_pk_fma_f32 v[108:109], v[68:69], v[90:91], v[108:109] op_sel_hi:[1,0,1]
	v_pk_fma_f32 v[106:107], v[70:71], v[78:79], v[106:107] op_sel:[0,1,0]
	v_pk_fma_f32 v[108:109], v[70:71], v[90:91], v[108:109] op_sel:[0,1,0]
	v_pk_mul_f32 v[110:111], v[64:65], v[72:73] op_sel_hi:[1,0]
	v_add_f32_dpp v106, v106, v106 quad_perm:[1,0,3,2] row_mask:0xf bank_mask:0xf bound_ctrl:1
	v_add_f32_dpp v107, v107, v107 quad_perm:[1,0,3,2] row_mask:0xf bank_mask:0xf bound_ctrl:1
	v_pk_fma_f32 v[108:109], v[94:95], v[176:177], v[108:109]
	v_pk_mul_f32 v[112:113], v[66:67], v[72:73] op_sel:[0,1]
	v_add_f32_dpp v106, v106, v106 quad_perm:[2,3,0,1] row_mask:0xf bank_mask:0xf bound_ctrl:1
	v_add_f32_dpp v107, v107, v107 quad_perm:[2,3,0,1] row_mask:0xf bank_mask:0xf bound_ctrl:1
	v_add_f32_dpp v149, v108, v108 row_half_mirror row_mask:0xf bank_mask:0xf bound_ctrl:1
	v_add_f32_dpp v149, v109, v109 row_half_mirror row_mask:0xf bank_mask:0xa
	v_add_f32_dpp v106, v106, v106 row_half_mirror row_mask:0xf bank_mask:0xf bound_ctrl:1
	v_add_f32_dpp v107, v107, v107 row_half_mirror row_mask:0xf bank_mask:0xf bound_ctrl:1
	v_pk_mul_f32 v[144:145], v[68:69], v[74:75] op_sel_hi:[1,0]
	v_pk_mul_f32 v[146:147], v[70:71], v[74:75] op_sel:[0,1]
	v_add_f32_dpp v150, v148, v148 row_ror:8 row_mask:0xf bank_mask:0xf bound_ctrl:1
	v_add_f32_dpp v150, v149, v149 row_ror:8 row_mask:0xf bank_mask:0xc
	v_add_f32_dpp v106, v106, v106 row_mirror row_mask:0xf bank_mask:0xf bound_ctrl:1
	v_add_f32_dpp v107, v107, v107 row_mirror row_mask:0xf bank_mask:0xf bound_ctrl:1
	v_pk_fma_f32 v[110:111], v[92:93], v[84:85], v[110:111] op_sel_hi:[1,0,1]
	v_pk_fma_f32 v[112:113], v[92:93], v[84:85], v[112:113] op_sel:[0,1,0]
	v_pk_fma_f32 v[144:145], v[92:93], v[86:87], v[144:145] op_sel_hi:[1,0,1]
	v_pk_fma_f32 v[146:147], v[92:93], v[86:87], v[146:147] op_sel:[0,1,0]
	v_add_f32_dpp v150, v150, v150 quad_perm:[1,0,3,2] row_mask:0xf bank_mask:0xf bound_ctrl:1
	v_pk_fma_f32 v[64:65], v[106:107], v[80:81], v[110:111] op_sel_hi:[1,0,1]
	v_pk_fma_f32 v[66:67], v[106:107], v[80:81], v[112:113] op_sel:[0,1,0]
	v_add_f32_dpp v150, v150, v150 quad_perm:[2,3,0,1] row_mask:0xf bank_mask:0xf bound_ctrl:1
	v_pk_fma_f32 v[68:69], v[106:107], v[82:83], v[144:145] op_sel_hi:[1,0,1]
	v_pk_fma_f32 v[70:71], v[106:107], v[82:83], v[146:147] op_sel:[0,1,0]
	s_mov_b64 exec, s[34:35]
	ds_write_b32 v178, v150 offset:1280
	s_mov_b64 exec, -1
	s_waitcnt lgkmcnt(1)
; #define SC_GET(X, t) do { const float* p = rec + (t) * 320; w##X = *(const f32x4*)p; a##X = *(const f32x4*)(p + 4); b##X = *(const f32x4*)(p + 8); k##X = *(const f32x4*)(p + 12); q##X = *(const f32x4*)(p + 16); \
;                 v##X = *(const f32x4*)(VVa + (t) * 64); } while (0)
; DI void scan_phase(unsigned char* lds, const Ctx& a, const Op& d, const int variant) {
;     ...
;                 SC_GET(A, 0);
; #pragma unroll 2
;                 for (int t = 0; t < SC_T; t += 2) {
;                     SC_GET(B, t + 1);
;                     SC_STEP(A, t);
;                     if (t + 2 < SC_T) SC_GET(A, t + 2);
;                     SC_STEP(B, t + 1);
;                 }
	ds_read_b128 v[72:75], v175 offset:16640
	ds_read_b128 v[76:79], v175 offset:16656
	ds_read_b128 v[80:83], v175 offset:16672
	ds_read_b128 v[84:87], v175 offset:16688
	ds_read_b128 v[88:91], v175 offset:16704
	ds_read_b128 v[92:95], v123 offset:44288
	v_pk_mul_f32 v[106:107], v[64:65], v[44:45] op_sel_hi:[1,0]
	v_pk_mul_f32 v[108:109], v[64:65], v[56:57] op_sel_hi:[1,0]
	v_pk_fma_f32 v[106:107], v[66:67], v[44:45], v[106:107] op_sel:[0,1,0]
	v_pk_fma_f32 v[108:109], v[66:67], v[56:57], v[108:109] op_sel:[0,1,0]
	v_pk_fma_f32 v[106:107], v[68:69], v[46:47], v[106:107] op_sel_hi:[1,0,1]
	v_pk_fma_f32 v[108:109], v[68:69], v[58:59], v[108:109] op_sel_hi:[1,0,1]
	v_pk_fma_f32 v[106:107], v[70:71], v[46:47], v[106:107] op_sel:[0,1,0]
	v_pk_fma_f32 v[108:109], v[70:71], v[58:59], v[108:109] op_sel:[0,1,0]
	v_pk_mul_f32 v[110:111], v[64:65], v[40:41] op_sel_hi:[1,0]
	v_add_f32_dpp v106, v106, v106 quad_perm:[1,0,3,2] row_mask:0xf bank_mask:0xf bound_ctrl:1
	v_add_f32_dpp v107, v107, v107 quad_perm:[1,0,3,2] row_mask:0xf bank_mask:0xf bound_ctrl:1
	v_pk_fma_f32 v[108:109], v[62:63], v[176:177], v[108:109]
	v_pk_mul_f32 v[112:113], v[66:67], v[40:41] op_sel:[0,1]
	v_add_f32_dpp v106, v106, v106 quad_perm:[2,3,0,1] row_mask:0xf bank_mask:0xf bound_ctrl:1
	v_add_f32_dpp v107, v107, v107 quad_perm:[2,3,0,1] row_mask:0xf bank_mask:0xf bound_ctrl:1
	v_add_f32_dpp v148, v108, v108 row_half_mirror row_mask:0xf bank_mask:0xf bound_ctrl:1
	v_add_f32_dpp v148, v109, v109 row_half_mirror row_mask:0xf bank_mask:0xa
	v_add_f32_dpp v106, v106, v106 row_half_mirror row_mask:0xf bank_mask:0xf bound_ctrl:1
	v_add_f32_dpp v107, v107, v107 row_half_mirror row_mask:0xf bank_mask:0xf bound_ctrl:1
	v_pk_mul_f32 v[144:145], v[68:69], v[42:43] op_sel_hi:[1,0]
	v_pk_mul_f32 v[146:147], v[70:71], v[42:43] op_sel:[0,1]
	v_add_f32_dpp v106, v106, v106 row_mirror row_mask:0xf bank_mask:0xf bound_ctrl:1
	v_add_f32_dpp v107, v107, v107 row_mirror row_mask:0xf bank_mask:0xf bound_ctrl:1
	v_pk_fma_f32 v[110:111], v[60:61], v[52:53], v[110:111] op_sel_hi:[1,0,1]
	v_pk_fma_f32 v[112:113], v[60:61], v[52:53], v[112:113] op_sel:[0,1,0]
	v_pk_fma_f32 v[144:145], v[60:61], v[54:55], v[144:145] op_sel_hi:[1,0,1]
	v_pk_fma_f32 v[146:147], v[60:61], v[54:55], v[146:147] op_sel:[0,1,0]
	v_pk_fma_f32 v[64:65], v[106:107], v[48:49], v[110:111] op_sel_hi:[1,0,1]
	v_pk_fma_f32 v[66:67], v[106:107], v[48:49], v[112:113] op_sel:[0,1,0]
	v_pk_fma_f32 v[68:69], v[106:107], v[50:51], v[144:145] op_sel_hi:[1,0,1]
	v_pk_fma_f32 v[70:71], v[106:107], v[50:51], v[146:147] op_sel:[0,1,0]
	s_waitcnt lgkmcnt(0)
	ds_read_b128 v[40:43], v175 offset:17920
	ds_read_b128 v[44:47], v175 offset:17936
	ds_read_b128 v[48:51], v175 offset:17952
	ds_read_b128 v[52:55], v175 offset:17968
	ds_read_b128 v[56:59], v175 offset:17984
	ds_read_b128 v[60:63], v123 offset:44544
	v_pk_mul_f32 v[106:107], v[64:65], v[76:77] op_sel_hi:[1,0]
	v_pk_mul_f32 v[108:109], v[64:65], v[88:89] op_sel_hi:[1,0]
	v_pk_fma_f32 v[106:107], v[66:67], v[76:77], v[106:107] op_sel:[0,1,0]
	v_pk_fma_f32 v[108:109], v[66:67], v[88:89], v[108:109] op_sel:[0,1,0]
	v_pk_fma_f32 v[106:107], v[68:69], v[78:79], v[106:107] op_sel_hi:[1,0,1]
	v_pk_fma_f32 v[108:109], v[68:69], v[90:91], v[108:109] op_sel_hi:[1,0,1]
	v_pk_fma_f32 v[106:107], v[70:71], v[78:79], v[106:107] op_sel:[0,1,0]
	v_pk_fma_f32 v[108:109], v[70:71], v[90:91], v[108:109] op_sel:[0,1,0]
	v_pk_mul_f32 v[110:111], v[64:65], v[72:73] op_sel_hi:[1,0]
	v_add_f32_dpp v106, v106, v106 quad_perm:[1,0,3,2] row_mask:0xf bank_mask:0xf bound_ctrl:1
	v_add_f32_dpp v107, v107, v107 quad_perm:[1,0,3,2] row_mask:0xf bank_mask:0xf bound_ctrl:1
	v_pk_fma_f32 v[108:109], v[94:95], v[176:177], v[108:109]
	v_pk_mul_f32 v[112:113], v[66:67], v[72:73] op_sel:[0,1]
	v_add_f32_dpp v106, v106, v106 quad_perm:[2,3,0,1] row_mask:0xf bank_mask:0xf bound_ctrl:1
	v_add_f32_dpp v107, v107, v107 quad_perm:[2,3,0,1] row_mask:0xf bank_mask:0xf bound_ctrl:1
	v_add_f32_dpp v149, v108, v108 row_half_mirror row_mask:0xf bank_mask:0xf bound_ctrl:1
	v_add_f32_dpp v149, v109, v109 row_half_mirror row_mask:0xf bank_mask:0xa
	v_add_f32_dpp v106, v106, v106 row_half_mirror row_mask:0xf bank_mask:0xf bound_ctrl:1
	v_add_f32_dpp v107, v107, v107 row_half_mirror row_mask:0xf bank_mask:0xf bound_ctrl:1
	v_pk_mul_f32 v[144:145], v[68:69], v[74:75] op_sel_hi:[1,0]
	v_pk_mul_f32 v[146:147], v[70:71], v[74:75] op_sel:[0,1]
	v_add_f32_dpp v150, v148, v148 row_ror:8 row_mask:0xf bank_mask:0xf bound_ctrl:1
	v_add_f32_dpp v150, v149, v149 row_ror:8 row_mask:0xf bank_mask:0xc
	v_add_f32_dpp v106, v106, v106 row_mirror row_mask:0xf bank_mask:0xf bound_ctrl:1
	v_add_f32_dpp v107, v107, v107 row_mirror row_mask:0xf bank_mask:0xf bound_ctrl:1
	v_pk_fma_f32 v[110:111], v[92:93], v[84:85], v[110:111] op_sel_hi:[1,0,1]
	v_pk_fma_f32 v[112:113], v[92:93], v[84:85], v[112:113] op_sel:[0,1,0]
	v_pk_fma_f32 v[144:145], v[92:93], v[86:87], v[144:145] op_sel_hi:[1,0,1]
	v_pk_fma_f32 v[146:147], v[92:93], v[86:87], v[146:147] op_sel:[0,1,0]
	v_add_f32_dpp v150, v150, v150 quad_perm:[1,0,3,2] row_mask:0xf bank_mask:0xf bound_ctrl:1
	v_pk_fma_f32 v[64:65], v[106:107], v[80:81], v[110:111] op_sel_hi:[1,0,1]
	v_pk_fma_f32 v[66:67], v[106:107], v[80:81], v[112:113] op_sel:[0,1,0]
	v_add_f32_dpp v150, v150, v150 quad_perm:[2,3,0,1] row_mask:0xf bank_mask:0xf bound_ctrl:1
	v_pk_fma_f32 v[68:69], v[106:107], v[82:83], v[144:145] op_sel_hi:[1,0,1]
	v_pk_fma_f32 v[70:71], v[106:107], v[82:83], v[146:147] op_sel:[0,1,0]
	s_mov_b64 exec, s[34:35]
	ds_write_b32 v178, v150 offset:1536
	s_mov_b64 exec, -1
	s_waitcnt lgkmcnt(1)
; #define SC_GET(X, t) do { const float* p = rec + (t) * 320; w##X = *(const f32x4*)p; a##X = *(const f32x4*)(p + 4); b##X = *(const f32x4*)(p + 8); k##X = *(const f32x4*)(p + 12); q##X = *(const f32x4*)(p + 16); \
;                 v##X = *(const f32x4*)(VVa + (t) * 64); } while (0)
; DI void scan_phase(unsigned char* lds, const Ctx& a, const Op& d, const int variant) {
;     ...
;                 SC_GET(A, 0);
; #pragma unroll 2
;                 for (int t = 0; t < SC_T; t += 2) {
;                     SC_GET(B, t + 1);
;                     SC_STEP(A, t);
;                     if (t + 2 < SC_T) SC_GET(A, t + 2);
;                     SC_STEP(B, t + 1);
;                 }
	ds_read_b128 v[72:75], v175 offset:19200
	ds_read_b128 v[76:79], v175 offset:19216
	ds_read_b128 v[80:83], v175 offset:19232
	ds_read_b128 v[84:87], v175 offset:19248
	ds_read_b128 v[88:91], v175 offset:19264
	ds_read_b128 v[92:95], v123 offset:44800
	v_pk_mul_f32 v[106:107], v[64:65], v[44:45] op_sel_hi:[1,0]
	v_pk_mul_f32 v[108:109], v[64:65], v[56:57] op_sel_hi:[1,0]
	v_pk_fma_f32 v[106:107], v[66:67], v[44:45], v[106:107] op_sel:[0,1,0]
	v_pk_fma_f32 v[108:109], v[66:67], v[56:57], v[108:109] op_sel:[0,1,0]
	v_pk_fma_f32 v[106:107], v[68:69], v[46:47], v[106:107] op_sel_hi:[1,0,1]
	v_pk_fma_f32 v[108:109], v[68:69], v[58:59], v[108:109] op_sel_hi:[1,0,1]
	v_pk_fma_f32 v[106:107], v[70:71], v[46:47], v[106:107] op_sel:[0,1,0]
	v_pk_fma_f32 v[108:109], v[70:71], v[58:59], v[108:109] op_sel:[0,1,0]
	v_pk_mul_f32 v[110:111], v[64:65], v[40:41] op_sel_hi:[1,0]
	v_add_f32_dpp v106, v106, v106 quad_perm:[1,0,3,2] row_mask:0xf bank_mask:0xf bound_ctrl:1
	v_add_f32_dpp v107, v107, v107 quad_perm:[1,0,3,2] row_mask:0xf bank_mask:0xf bound_ctrl:1
	v_pk_fma_f32 v[108:109], v[62:63], v[176:177], v[108:109]
	v_pk_mul_f32 v[112:113], v[66:67], v[40:41] op_sel:[0,1]
	v_add_f32_dpp v106, v106, v106 quad_perm:[2,3,0,1] row_mask:0xf bank_mask:0xf bound_ctrl:1
	v_add_f32_dpp v107, v107, v107 quad_perm:[2,3,0,1] row_mask:0xf bank_mask:0xf bound_ctrl:1
	v_add_f32_dpp v148, v108, v108 row_half_mirror row_mask:0xf bank_mask:0xf bound_ctrl:1
	v_add_f32_dpp v148, v109, v109 row_half_mirror row_mask:0xf bank_mask:0xa
	v_add_f32_dpp v106, v106, v106 row_half_mirror row_mask:0xf bank_mask:0xf bound_ctrl:1
	v_add_f32_dpp v107, v107, v107 row_half_mirror row_mask:0xf bank_mask:0xf bound_ctrl:1
	v_pk_mul_f32 v[144:145], v[68:69], v[42:43] op_sel_hi:[1,0]
	v_pk_mul_f32 v[146:147], v[70:71], v[42:43] op_sel:[0,1]
	v_add_f32_dpp v106, v106, v106 row_mirror row_mask:0xf bank_mask:0xf bound_ctrl:1
	v_add_f32_dpp v107, v107, v107 row_mirror row_mask:0xf bank_mask:0xf bound_ctrl:1
	v_pk_fma_f32 v[110:111], v[60:61], v[52:53], v[110:111] op_sel_hi:[1,0,1]
	v_pk_fma_f32 v[112:113], v[60:61], v[52:53], v[112:113] op_sel:[0,1,0]
	v_pk_fma_f32 v[144:145], v[60:61], v[54:55], v[144:145] op_sel_hi:[1,0,1]
	v_pk_fma_f32 v[146:147], v[60:61], v[54:55], v[146:147] op_sel:[0,1,0]
	v_pk_fma_f32 v[64:65], v[106:107], v[48:49], v[110:111] op_sel_hi:[1,0,1]
	v_pk_fma_f32 v[66:67], v[106:107], v[48:49], v[112:113] op_sel:[0,1,0]
	v_pk_fma_f32 v[68:69], v[106:107], v[50:51], v[144:145] op_sel_hi:[1,0,1]
	v_pk_fma_f32 v[70:71], v[106:107], v[50:51], v[146:147] op_sel:[0,1,0]
	s_waitcnt lgkmcnt(0)
	ds_read_b128 v[40:43], v175 offset:20480
	ds_read_b128 v[44:47], v175 offset:20496
	ds_read_b128 v[48:51], v175 offset:20512
	ds_read_b128 v[52:55], v175 offset:20528
	ds_read_b128 v[56:59], v175 offset:20544
	ds_read_b128 v[60:63], v123 offset:45056
	v_pk_mul_f32 v[106:107], v[64:65], v[76:77] op_sel_hi:[1,0]
	v_pk_mul_f32 v[108:109], v[64:65], v[88:89] op_sel_hi:[1,0]
	v_pk_fma_f32 v[106:107], v[66:67], v[76:77], v[106:107] op_sel:[0,1,0]
	v_pk_fma_f32 v[108:109], v[66:67], v[88:89], v[108:109] op_sel:[0,1,0]
	v_pk_fma_f32 v[106:107], v[68:69], v[78:79], v[106:107] op_sel_hi:[1,0,1]
	v_pk_fma_f32 v[108:109], v[68:69], v[90:91], v[108:109] op_sel_hi:[1,0,1]
	v_pk_fma_f32 v[106:107], v[70:71], v[78:79], v[106:107] op_sel:[0,1,0]
	v_pk_fma_f32 v[108:109], v[70:71], v[90:91], v[108:109] op_sel:[0,1,0]
	v_pk_mul_f32 v[110:111], v[64:65], v[72:73] op_sel_hi:[1,0]
	v_add_f32_dpp v106, v106, v106 quad_perm:[1,0,3,2] row_mask:0xf bank_mask:0xf bound_ctrl:1
	v_add_f32_dpp v107, v107, v107 quad_perm:[1,0,3,2] row_mask:0xf bank_mask:0xf bound_ctrl:1
	v_pk_fma_f32 v[108:109], v[94:95], v[176:177], v[108:109]
	v_pk_mul_f32 v[112:113], v[66:67], v[72:73] op_sel:[0,1]
	v_add_f32_dpp v106, v106, v106 quad_perm:[2,3,0,1] row_mask:0xf bank_mask:0xf bound_ctrl:1
	v_add_f32_dpp v107, v107, v107 quad_perm:[2,3,0,1] row_mask:0xf bank_mask:0xf bound_ctrl:1
	v_add_f32_dpp v149, v108, v108 row_half_mirror row_mask:0xf bank_mask:0xf bound_ctrl:1
	v_add_f32_dpp v149, v109, v109 row_half_mirror row_mask:0xf bank_mask:0xa
	v_add_f32_dpp v106, v106, v106 row_half_mirror row_mask:0xf bank_mask:0xf bound_ctrl:1
	v_add_f32_dpp v107, v107, v107 row_half_mirror row_mask:0xf bank_mask:0xf bound_ctrl:1
	v_pk_mul_f32 v[144:145], v[68:69], v[74:75] op_sel_hi:[1,0]
	v_pk_mul_f32 v[146:147], v[70:71], v[74:75] op_sel:[0,1]
	v_add_f32_dpp v150, v148, v148 row_ror:8 row_mask:0xf bank_mask:0xf bound_ctrl:1
	v_add_f32_dpp v150, v149, v149 row_ror:8 row_mask:0xf bank_mask:0xc
	v_add_f32_dpp v106, v106, v106 row_mirror row_mask:0xf bank_mask:0xf bound_ctrl:1
	v_add_f32_dpp v107, v107, v107 row_mirror row_mask:0xf bank_mask:0xf bound_ctrl:1
	v_pk_fma_f32 v[110:111], v[92:93], v[84:85], v[110:111] op_sel_hi:[1,0,1]
	v_pk_fma_f32 v[112:113], v[92:93], v[84:85], v[112:113] op_sel:[0,1,0]
	v_pk_fma_f32 v[144:145], v[92:93], v[86:87], v[144:145] op_sel_hi:[1,0,1]
	v_pk_fma_f32 v[146:147], v[92:93], v[86:87], v[146:147] op_sel:[0,1,0]
	v_add_f32_dpp v150, v150, v150 quad_perm:[1,0,3,2] row_mask:0xf bank_mask:0xf bound_ctrl:1
	v_pk_fma_f32 v[64:65], v[106:107], v[80:81], v[110:111] op_sel_hi:[1,0,1]
	v_pk_fma_f32 v[66:67], v[106:107], v[80:81], v[112:113] op_sel:[0,1,0]
	v_add_f32_dpp v150, v150, v150 quad_perm:[2,3,0,1] row_mask:0xf bank_mask:0xf bound_ctrl:1
	v_pk_fma_f32 v[68:69], v[106:107], v[82:83], v[144:145] op_sel_hi:[1,0,1]
	v_pk_fma_f32 v[70:71], v[106:107], v[82:83], v[146:147] op_sel:[0,1,0]
	s_mov_b64 exec, s[34:35]
	ds_write_b32 v178, v150 offset:1792
	s_mov_b64 exec, -1
	s_waitcnt lgkmcnt(1)
; #define SC_GET(X, t) do { const float* p = rec + (t) * 320; w##X = *(const f32x4*)p; a##X = *(const f32x4*)(p + 4); b##X = *(const f32x4*)(p + 8); k##X = *(const f32x4*)(p + 12); q##X = *(const f32x4*)(p + 16); \
;                 v##X = *(const f32x4*)(VVa + (t) * 64); } while (0)
; DI void scan_phase(unsigned char* lds, const Ctx& a, const Op& d, const int variant) {
;     ...
;                 SC_GET(A, 0);
; #pragma unroll 2
;                 for (int t = 0; t < SC_T; t += 2) {
;                     SC_GET(B, t + 1);
;                     SC_STEP(A, t);
;                     if (t + 2 < SC_T) SC_GET(A, t + 2);
;                     SC_STEP(B, t + 1);
;                 }
	ds_read_b128 v[72:75], v175 offset:21760
	ds_read_b128 v[76:79], v175 offset:21776
	ds_read_b128 v[80:83], v175 offset:21792
	ds_read_b128 v[84:87], v175 offset:21808
	ds_read_b128 v[88:91], v175 offset:21824
	ds_read_b128 v[92:95], v123 offset:45312
	v_pk_mul_f32 v[106:107], v[64:65], v[44:45] op_sel_hi:[1,0]
	v_pk_mul_f32 v[108:109], v[64:65], v[56:57] op_sel_hi:[1,0]
	v_pk_fma_f32 v[106:107], v[66:67], v[44:45], v[106:107] op_sel:[0,1,0]
	v_pk_fma_f32 v[108:109], v[66:67], v[56:57], v[108:109] op_sel:[0,1,0]
	v_pk_fma_f32 v[106:107], v[68:69], v[46:47], v[106:107] op_sel_hi:[1,0,1]
	v_pk_fma_f32 v[108:109], v[68:69], v[58:59], v[108:109] op_sel_hi:[1,0,1]
	v_pk_fma_f32 v[106:107], v[70:71], v[46:47], v[106:107] op_sel:[0,1,0]
	v_pk_fma_f32 v[108:109], v[70:71], v[58:59], v[108:109] op_sel:[0,1,0]
	v_pk_mul_f32 v[110:111], v[64:65], v[40:41] op_sel_hi:[1,0]
	v_add_f32_dpp v106, v106, v106 quad_perm:[1,0,3,2] row_mask:0xf bank_mask:0xf bound_ctrl:1
	v_add_f32_dpp v107, v107, v107 quad_perm:[1,0,3,2] row_mask:0xf bank_mask:0xf bound_ctrl:1
	v_pk_fma_f32 v[108:109], v[62:63], v[176:177], v[108:109]
	v_pk_mul_f32 v[112:113], v[66:67], v[40:41] op_sel:[0,1]
	v_add_f32_dpp v106, v106, v106 quad_perm:[2,3,0,1] row_mask:0xf bank_mask:0xf bound_ctrl:1
	v_add_f32_dpp v107, v107, v107 quad_perm:[2,3,0,1] row_mask:0xf bank_mask:0xf bound_ctrl:1
	v_add_f32_dpp v148, v108, v108 row_half_mirror row_mask:0xf bank_mask:0xf bound_ctrl:1
	v_add_f32_dpp v148, v109, v109 row_half_mirror row_mask:0xf bank_mask:0xa
	v_add_f32_dpp v106, v106, v106 row_half_mirror row_mask:0xf bank_mask:0xf bound_ctrl:1
	v_add_f32_dpp v107, v107, v107 row_half_mirror row_mask:0xf bank_mask:0xf bound_ctrl:1
	v_pk_mul_f32 v[144:145], v[68:69], v[42:43] op_sel_hi:[1,0]
	v_pk_mul_f32 v[146:147], v[70:71], v[42:43] op_sel:[0,1]
	v_add_f32_dpp v106, v106, v106 row_mirror row_mask:0xf bank_mask:0xf bound_ctrl:1
	v_add_f32_dpp v107, v107, v107 row_mirror row_mask:0xf bank_mask:0xf bound_ctrl:1
	v_pk_fma_f32 v[110:111], v[60:61], v[52:53], v[110:111] op_sel_hi:[1,0,1]
	v_pk_fma_f32 v[112:113], v[60:61], v[52:53], v[112:113] op_sel:[0,1,0]
	v_pk_fma_f32 v[144:145], v[60:61], v[54:55], v[144:145] op_sel_hi:[1,0,1]
	v_pk_fma_f32 v[146:147], v[60:61], v[54:55], v[146:147] op_sel:[0,1,0]
	v_pk_fma_f32 v[64:65], v[106:107], v[48:49], v[110:111] op_sel_hi:[1,0,1]
	v_pk_fma_f32 v[66:67], v[106:107], v[48:49], v[112:113] op_sel:[0,1,0]
	v_pk_fma_f32 v[68:69], v[106:107], v[50:51], v[144:145] op_sel_hi:[1,0,1]
	v_pk_fma_f32 v[70:71], v[106:107], v[50:51], v[146:147] op_sel:[0,1,0]
	s_waitcnt lgkmcnt(0)
	ds_read_b128 v[40:43], v175 offset:23040
	ds_read_b128 v[44:47], v175 offset:23056
	ds_read_b128 v[48:51], v175 offset:23072
	ds_read_b128 v[52:55], v175 offset:23088
	ds_read_b128 v[56:59], v175 offset:23104
	ds_read_b128 v[60:63], v123 offset:45568
	v_pk_mul_f32 v[106:107], v[64:65], v[76:77] op_sel_hi:[1,0]
	v_pk_mul_f32 v[108:109], v[64:65], v[88:89] op_sel_hi:[1,0]
	v_pk_fma_f32 v[106:107], v[66:67], v[76:77], v[106:107] op_sel:[0,1,0]
	v_pk_fma_f32 v[108:109], v[66:67], v[88:89], v[108:109] op_sel:[0,1,0]
	v_pk_fma_f32 v[106:107], v[68:69], v[78:79], v[106:107] op_sel_hi:[1,0,1]
	v_pk_fma_f32 v[108:109], v[68:69], v[90:91], v[108:109] op_sel_hi:[1,0,1]
	v_pk_fma_f32 v[106:107], v[70:71], v[78:79], v[106:107] op_sel:[0,1,0]
	v_pk_fma_f32 v[108:109], v[70:71], v[90:91], v[108:109] op_sel:[0,1,0]
	v_pk_mul_f32 v[110:111], v[64:65], v[72:73] op_sel_hi:[1,0]
	v_add_f32_dpp v106, v106, v106 quad_perm:[1,0,3,2] row_mask:0xf bank_mask:0xf bound_ctrl:1
	v_add_f32_dpp v107, v107, v107 quad_perm:[1,0,3,2] row_mask:0xf bank_mask:0xf bound_ctrl:1
	v_pk_fma_f32 v[108:109], v[94:95], v[176:177], v[108:109]
	v_pk_mul_f32 v[112:113], v[66:67], v[72:73] op_sel:[0,1]
	v_add_f32_dpp v106, v106, v106 quad_perm:[2,3,0,1] row_mask:0xf bank_mask:0xf bound_ctrl:1
	v_add_f32_dpp v107, v107, v107 quad_perm:[2,3,0,1] row_mask:0xf bank_mask:0xf bound_ctrl:1
	v_add_f32_dpp v149, v108, v108 row_half_mirror row_mask:0xf bank_mask:0xf bound_ctrl:1
	v_add_f32_dpp v149, v109, v109 row_half_mirror row_mask:0xf bank_mask:0xa
	v_add_f32_dpp v106, v106, v106 row_half_mirror row_mask:0xf bank_mask:0xf bound_ctrl:1
	v_add_f32_dpp v107, v107, v107 row_half_mirror row_mask:0xf bank_mask:0xf bound_ctrl:1
	v_pk_mul_f32 v[144:145], v[68:69], v[74:75] op_sel_hi:[1,0]
	v_pk_mul_f32 v[146:147], v[70:71], v[74:75] op_sel:[0,1]
	v_add_f32_dpp v150, v148, v148 row_ror:8 row_mask:0xf bank_mask:0xf bound_ctrl:1
	v_add_f32_dpp v150, v149, v149 row_ror:8 row_mask:0xf bank_mask:0xc
	v_add_f32_dpp v106, v106, v106 row_mirror row_mask:0xf bank_mask:0xf bound_ctrl:1
	v_add_f32_dpp v107, v107, v107 row_mirror row_mask:0xf bank_mask:0xf bound_ctrl:1
	v_pk_fma_f32 v[110:111], v[92:93], v[84:85], v[110:111] op_sel_hi:[1,0,1]
	v_pk_fma_f32 v[112:113], v[92:93], v[84:85], v[112:113] op_sel:[0,1,0]
	v_pk_fma_f32 v[144:145], v[92:93], v[86:87], v[144:145] op_sel_hi:[1,0,1]
	v_pk_fma_f32 v[146:147], v[92:93], v[86:87], v[146:147] op_sel:[0,1,0]
	v_add_f32_dpp v150, v150, v150 quad_perm:[1,0,3,2] row_mask:0xf bank_mask:0xf bound_ctrl:1
	v_pk_fma_f32 v[64:65], v[106:107], v[80:81], v[110:111] op_sel_hi:[1,0,1]
	v_pk_fma_f32 v[66:67], v[106:107], v[80:81], v[112:113] op_sel:[0,1,0]
	v_add_f32_dpp v150, v150, v150 quad_perm:[2,3,0,1] row_mask:0xf bank_mask:0xf bound_ctrl:1
	v_pk_fma_f32 v[68:69], v[106:107], v[82:83], v[144:145] op_sel_hi:[1,0,1]
	v_pk_fma_f32 v[70:71], v[106:107], v[82:83], v[146:147] op_sel:[0,1,0]
	s_mov_b64 exec, s[34:35]
	ds_write_b32 v178, v150 offset:2048
	s_mov_b64 exec, -1
	s_waitcnt lgkmcnt(1)
; #define SC_GET(X, t) do { const float* p = rec + (t) * 320; w##X = *(const f32x4*)p; a##X = *(const f32x4*)(p + 4); b##X = *(const f32x4*)(p + 8); k##X = *(const f32x4*)(p + 12); q##X = *(const f32x4*)(p + 16); \
;                 v##X = *(const f32x4*)(VVa + (t) * 64); } while (0)
; DI void scan_phase(unsigned char* lds, const Ctx& a, const Op& d, const int variant) {
;     ...
;                 SC_GET(A, 0);
; #pragma unroll 2
;                 for (int t = 0; t < SC_T; t += 2) {
;                     SC_GET(B, t + 1);
;                     SC_STEP(A, t);
;                     if (t + 2 < SC_T) SC_GET(A, t + 2);
;                     SC_STEP(B, t + 1);
;                 }
	ds_read_b128 v[72:75], v175 offset:24320
	ds_read_b128 v[76:79], v175 offset:24336
	ds_read_b128 v[80:83], v175 offset:24352
	ds_read_b128 v[84:87], v175 offset:24368
	ds_read_b128 v[88:91], v175 offset:24384
	ds_read_b128 v[92:95], v123 offset:45824
	v_pk_mul_f32 v[106:107], v[64:65], v[44:45] op_sel_hi:[1,0]
	v_pk_mul_f32 v[108:109], v[64:65], v[56:57] op_sel_hi:[1,0]
	v_pk_fma_f32 v[106:107], v[66:67], v[44:45], v[106:107] op_sel:[0,1,0]
	v_pk_fma_f32 v[108:109], v[66:67], v[56:57], v[108:109] op_sel:[0,1,0]
	v_pk_fma_f32 v[106:107], v[68:69], v[46:47], v[106:107] op_sel_hi:[1,0,1]
	v_pk_fma_f32 v[108:109], v[68:69], v[58:59], v[108:109] op_sel_hi:[1,0,1]
	v_pk_fma_f32 v[106:107], v[70:71], v[46:47], v[106:107] op_sel:[0,1,0]
	v_pk_fma_f32 v[108:109], v[70:71], v[58:59], v[108:109] op_sel:[0,1,0]
	v_pk_mul_f32 v[110:111], v[64:65], v[40:41] op_sel_hi:[1,0]
	v_add_f32_dpp v106, v106, v106 quad_perm:[1,0,3,2] row_mask:0xf bank_mask:0xf bound_ctrl:1
	v_add_f32_dpp v107, v107, v107 quad_perm:[1,0,3,2] row_mask:0xf bank_mask:0xf bound_ctrl:1
	v_pk_fma_f32 v[108:109], v[62:63], v[176:177], v[108:109]
	v_pk_mul_f32 v[112:113], v[66:67], v[40:41] op_sel:[0,1]
	v_add_f32_dpp v106, v106, v106 quad_perm:[2,3,0,1] row_mask:0xf bank_mask:0xf bound_ctrl:1
	v_add_f32_dpp v107, v107, v107 quad_perm:[2,3,0,1] row_mask:0xf bank_mask:0xf bound_ctrl:1
	v_add_f32_dpp v148, v108, v108 row_half_mirror row_mask:0xf bank_mask:0xf bound_ctrl:1
	v_add_f32_dpp v148, v109, v109 row_half_mirror row_mask:0xf bank_mask:0xa
	v_add_f32_dpp v106, v106, v106 row_half_mirror row_mask:0xf bank_mask:0xf bound_ctrl:1
	v_add_f32_dpp v107, v107, v107 row_half_mirror row_mask:0xf bank_mask:0xf bound_ctrl:1
	v_pk_mul_f32 v[144:145], v[68:69], v[42:43] op_sel_hi:[1,0]
	v_pk_mul_f32 v[146:147], v[70:71], v[42:43] op_sel:[0,1]
	v_add_f32_dpp v106, v106, v106 row_mirror row_mask:0xf bank_mask:0xf bound_ctrl:1
	v_add_f32_dpp v107, v107, v107 row_mirror row_mask:0xf bank_mask:0xf bound_ctrl:1
	v_pk_fma_f32 v[110:111], v[60:61], v[52:53], v[110:111] op_sel_hi:[1,0,1]
	v_pk_fma_f32 v[112:113], v[60:61], v[52:53], v[112:113] op_sel:[0,1,0]
	v_pk_fma_f32 v[144:145], v[60:61], v[54:55], v[144:145] op_sel_hi:[1,0,1]
	v_pk_fma_f32 v[146:147], v[60:61], v[54:55], v[146:147] op_sel:[0,1,0]
	v_pk_fma_f32 v[64:65], v[106:107], v[48:49], v[110:111] op_sel_hi:[1,0,1]
	v_pk_fma_f32 v[66:67], v[106:107], v[48:49], v[112:113] op_sel:[0,1,0]
	v_pk_fma_f32 v[68:69], v[106:107], v[50:51], v[144:145] op_sel_hi:[1,0,1]
	v_pk_fma_f32 v[70:71], v[106:107], v[50:51], v[146:147] op_sel:[0,1,0]
	s_waitcnt lgkmcnt(0)
	ds_read_b128 v[40:43], v175 offset:25600
	ds_read_b128 v[44:47], v175 offset:25616
	ds_read_b128 v[48:51], v175 offset:25632
	ds_read_b128 v[52:55], v175 offset:25648
	ds_read_b128 v[56:59], v175 offset:25664
	ds_read_b128 v[60:63], v123 offset:46080
	v_pk_mul_f32 v[106:107], v[64:65], v[76:77] op_sel_hi:[1,0]
	v_pk_mul_f32 v[108:109], v[64:65], v[88:89] op_sel_hi:[1,0]
	v_pk_fma_f32 v[106:107], v[66:67], v[76:77], v[106:107] op_sel:[0,1,0]
	v_pk_fma_f32 v[108:109], v[66:67], v[88:89], v[108:109] op_sel:[0,1,0]
	v_pk_fma_f32 v[106:107], v[68:69], v[78:79], v[106:107] op_sel_hi:[1,0,1]
	v_pk_fma_f32 v[108:109], v[68:69], v[90:91], v[108:109] op_sel_hi:[1,0,1]
	v_pk_fma_f32 v[106:107], v[70:71], v[78:79], v[106:107] op_sel:[0,1,0]
	v_pk_fma_f32 v[108:109], v[70:71], v[90:91], v[108:109] op_sel:[0,1,0]
	v_pk_mul_f32 v[110:111], v[64:65], v[72:73] op_sel_hi:[1,0]
	v_add_f32_dpp v106, v106, v106 quad_perm:[1,0,3,2] row_mask:0xf bank_mask:0xf bound_ctrl:1
	v_add_f32_dpp v107, v107, v107 quad_perm:[1,0,3,2] row_mask:0xf bank_mask:0xf bound_ctrl:1
	v_pk_fma_f32 v[108:109], v[94:95], v[176:177], v[108:109]
	v_pk_mul_f32 v[112:113], v[66:67], v[72:73] op_sel:[0,1]
	v_add_f32_dpp v106, v106, v106 quad_perm:[2,3,0,1] row_mask:0xf bank_mask:0xf bound_ctrl:1
	v_add_f32_dpp v107, v107, v107 quad_perm:[2,3,0,1] row_mask:0xf bank_mask:0xf bound_ctrl:1
	v_add_f32_dpp v149, v108, v108 row_half_mirror row_mask:0xf bank_mask:0xf bound_ctrl:1
	v_add_f32_dpp v149, v109, v109 row_half_mirror row_mask:0xf bank_mask:0xa
	v_add_f32_dpp v106, v106, v106 row_half_mirror row_mask:0xf bank_mask:0xf bound_ctrl:1
	v_add_f32_dpp v107, v107, v107 row_half_mirror row_mask:0xf bank_mask:0xf bound_ctrl:1
	v_pk_mul_f32 v[144:145], v[68:69], v[74:75] op_sel_hi:[1,0]
	v_pk_mul_f32 v[146:147], v[70:71], v[74:75] op_sel:[0,1]
	v_add_f32_dpp v150, v148, v148 row_ror:8 row_mask:0xf bank_mask:0xf bound_ctrl:1
	v_add_f32_dpp v150, v149, v149 row_ror:8 row_mask:0xf bank_mask:0xc
	v_add_f32_dpp v106, v106, v106 row_mirror row_mask:0xf bank_mask:0xf bound_ctrl:1
	v_add_f32_dpp v107, v107, v107 row_mirror row_mask:0xf bank_mask:0xf bound_ctrl:1
	v_pk_fma_f32 v[110:111], v[92:93], v[84:85], v[110:111] op_sel_hi:[1,0,1]
	v_pk_fma_f32 v[112:113], v[92:93], v[84:85], v[112:113] op_sel:[0,1,0]
	v_pk_fma_f32 v[144:145], v[92:93], v[86:87], v[144:145] op_sel_hi:[1,0,1]
	v_pk_fma_f32 v[146:147], v[92:93], v[86:87], v[146:147] op_sel:[0,1,0]
	v_add_f32_dpp v150, v150, v150 quad_perm:[1,0,3,2] row_mask:0xf bank_mask:0xf bound_ctrl:1
	v_pk_fma_f32 v[64:65], v[106:107], v[80:81], v[110:111] op_sel_hi:[1,0,1]
	v_pk_fma_f32 v[66:67], v[106:107], v[80:81], v[112:113] op_sel:[0,1,0]
	v_add_f32_dpp v150, v150, v150 quad_perm:[2,3,0,1] row_mask:0xf bank_mask:0xf bound_ctrl:1
	v_pk_fma_f32 v[68:69], v[106:107], v[82:83], v[144:145] op_sel_hi:[1,0,1]
	v_pk_fma_f32 v[70:71], v[106:107], v[82:83], v[146:147] op_sel:[0,1,0]
	s_mov_b64 exec, s[34:35]
	ds_write_b32 v178, v150 offset:2304
	s_mov_b64 exec, -1
	s_waitcnt lgkmcnt(1)
; #define SC_GET(X, t) do { const float* p = rec + (t) * 320; w##X = *(const f32x4*)p; a##X = *(const f32x4*)(p + 4); b##X = *(const f32x4*)(p + 8); k##X = *(const f32x4*)(p + 12); q##X = *(const f32x4*)(p + 16); \
;                 v##X = *(const f32x4*)(VVa + (t) * 64); } while (0)
; DI void scan_phase(unsigned char* lds, const Ctx& a, const Op& d, const int variant) {
;     ...
;                 SC_GET(A, 0);
; #pragma unroll 2
;                 for (int t = 0; t < SC_T; t += 2) {
;                     SC_GET(B, t + 1);
;                     SC_STEP(A, t);
;                     if (t + 2 < SC_T) SC_GET(A, t + 2);
;                     SC_STEP(B, t + 1);
;                 }
	ds_read_b128 v[72:75], v175 offset:26880
	ds_read_b128 v[76:79], v175 offset:26896
	ds_read_b128 v[80:83], v175 offset:26912
	ds_read_b128 v[84:87], v175 offset:26928
	ds_read_b128 v[88:91], v175 offset:26944
	ds_read_b128 v[92:95], v123 offset:46336
	v_pk_mul_f32 v[106:107], v[64:65], v[44:45] op_sel_hi:[1,0]
	v_pk_mul_f32 v[108:109], v[64:65], v[56:57] op_sel_hi:[1,0]
	v_pk_fma_f32 v[106:107], v[66:67], v[44:45], v[106:107] op_sel:[0,1,0]
	v_pk_fma_f32 v[108:109], v[66:67], v[56:57], v[108:109] op_sel:[0,1,0]
	v_pk_fma_f32 v[106:107], v[68:69], v[46:47], v[106:107] op_sel_hi:[1,0,1]
	v_pk_fma_f32 v[108:109], v[68:69], v[58:59], v[108:109] op_sel_hi:[1,0,1]
	v_pk_fma_f32 v[106:107], v[70:71], v[46:47], v[106:107] op_sel:[0,1,0]
	v_pk_fma_f32 v[108:109], v[70:71], v[58:59], v[108:109] op_sel:[0,1,0]
	v_pk_mul_f32 v[110:111], v[64:65], v[40:41] op_sel_hi:[1,0]
	v_add_f32_dpp v106, v106, v106 quad_perm:[1,0,3,2] row_mask:0xf bank_mask:0xf bound_ctrl:1
	v_add_f32_dpp v107, v107, v107 quad_perm:[1,0,3,2] row_mask:0xf bank_mask:0xf bound_ctrl:1
	v_pk_fma_f32 v[108:109], v[62:63], v[176:177], v[108:109]
	v_pk_mul_f32 v[112:113], v[66:67], v[40:41] op_sel:[0,1]
	v_add_f32_dpp v106, v106, v106 quad_perm:[2,3,0,1] row_mask:0xf bank_mask:0xf bound_ctrl:1
	v_add_f32_dpp v107, v107, v107 quad_perm:[2,3,0,1] row_mask:0xf bank_mask:0xf bound_ctrl:1
	v_add_f32_dpp v148, v108, v108 row_half_mirror row_mask:0xf bank_mask:0xf bound_ctrl:1
	v_add_f32_dpp v148, v109, v109 row_half_mirror row_mask:0xf bank_mask:0xa
	v_add_f32_dpp v106, v106, v106 row_half_mirror row_mask:0xf bank_mask:0xf bound_ctrl:1
	v_add_f32_dpp v107, v107, v107 row_half_mirror row_mask:0xf bank_mask:0xf bound_ctrl:1
	v_pk_mul_f32 v[144:145], v[68:69], v[42:43] op_sel_hi:[1,0]
	v_pk_mul_f32 v[146:147], v[70:71], v[42:43] op_sel:[0,1]
	v_add_f32_dpp v106, v106, v106 row_mirror row_mask:0xf bank_mask:0xf bound_ctrl:1
	v_add_f32_dpp v107, v107, v107 row_mirror row_mask:0xf bank_mask:0xf bound_ctrl:1
	v_pk_fma_f32 v[110:111], v[60:61], v[52:53], v[110:111] op_sel_hi:[1,0,1]
	v_pk_fma_f32 v[112:113], v[60:61], v[52:53], v[112:113] op_sel:[0,1,0]
	v_pk_fma_f32 v[144:145], v[60:61], v[54:55], v[144:145] op_sel_hi:[1,0,1]
	v_pk_fma_f32 v[146:147], v[60:61], v[54:55], v[146:147] op_sel:[0,1,0]
	v_pk_fma_f32 v[64:65], v[106:107], v[48:49], v[110:111] op_sel_hi:[1,0,1]
	v_pk_fma_f32 v[66:67], v[106:107], v[48:49], v[112:113] op_sel:[0,1,0]
	v_pk_fma_f32 v[68:69], v[106:107], v[50:51], v[144:145] op_sel_hi:[1,0,1]
	v_pk_fma_f32 v[70:71], v[106:107], v[50:51], v[146:147] op_sel:[0,1,0]
	s_waitcnt lgkmcnt(0)
	ds_read_b128 v[40:43], v175 offset:28160
	ds_read_b128 v[44:47], v175 offset:28176
	ds_read_b128 v[48:51], v175 offset:28192
	ds_read_b128 v[52:55], v175 offset:28208
	ds_read_b128 v[56:59], v175 offset:28224
	ds_read_b128 v[60:63], v123 offset:46592
	v_pk_mul_f32 v[106:107], v[64:65], v[76:77] op_sel_hi:[1,0]
	v_pk_mul_f32 v[108:109], v[64:65], v[88:89] op_sel_hi:[1,0]
	v_pk_fma_f32 v[106:107], v[66:67], v[76:77], v[106:107] op_sel:[0,1,0]
	v_pk_fma_f32 v[108:109], v[66:67], v[88:89], v[108:109] op_sel:[0,1,0]
	v_pk_fma_f32 v[106:107], v[68:69], v[78:79], v[106:107] op_sel_hi:[1,0,1]
	v_pk_fma_f32 v[108:109], v[68:69], v[90:91], v[108:109] op_sel_hi:[1,0,1]
	v_pk_fma_f32 v[106:107], v[70:71], v[78:79], v[106:107] op_sel:[0,1,0]
	v_pk_fma_f32 v[108:109], v[70:71], v[90:91], v[108:109] op_sel:[0,1,0]
	v_pk_mul_f32 v[110:111], v[64:65], v[72:73] op_sel_hi:[1,0]
	v_add_f32_dpp v106, v106, v106 quad_perm:[1,0,3,2] row_mask:0xf bank_mask:0xf bound_ctrl:1
	v_add_f32_dpp v107, v107, v107 quad_perm:[1,0,3,2] row_mask:0xf bank_mask:0xf bound_ctrl:1
	v_pk_fma_f32 v[108:109], v[94:95], v[176:177], v[108:109]
	v_pk_mul_f32 v[112:113], v[66:67], v[72:73] op_sel:[0,1]
	v_add_f32_dpp v106, v106, v106 quad_perm:[2,3,0,1] row_mask:0xf bank_mask:0xf bound_ctrl:1
	v_add_f32_dpp v107, v107, v107 quad_perm:[2,3,0,1] row_mask:0xf bank_mask:0xf bound_ctrl:1
	v_add_f32_dpp v149, v108, v108 row_half_mirror row_mask:0xf bank_mask:0xf bound_ctrl:1
	v_add_f32_dpp v149, v109, v109 row_half_mirror row_mask:0xf bank_mask:0xa
	v_add_f32_dpp v106, v106, v106 row_half_mirror row_mask:0xf bank_mask:0xf bound_ctrl:1
	v_add_f32_dpp v107, v107, v107 row_half_mirror row_mask:0xf bank_mask:0xf bound_ctrl:1
	v_pk_mul_f32 v[144:145], v[68:69], v[74:75] op_sel_hi:[1,0]
	v_pk_mul_f32 v[146:147], v[70:71], v[74:75] op_sel:[0,1]
	v_add_f32_dpp v150, v148, v148 row_ror:8 row_mask:0xf bank_mask:0xf bound_ctrl:1
	v_add_f32_dpp v150, v149, v149 row_ror:8 row_mask:0xf bank_mask:0xc
	v_add_f32_dpp v106, v106, v106 row_mirror row_mask:0xf bank_mask:0xf bound_ctrl:1
	v_add_f32_dpp v107, v107, v107 row_mirror row_mask:0xf bank_mask:0xf bound_ctrl:1
	v_pk_fma_f32 v[110:111], v[92:93], v[84:85], v[110:111] op_sel_hi:[1,0,1]
	v_pk_fma_f32 v[112:113], v[92:93], v[84:85], v[112:113] op_sel:[0,1,0]
	v_pk_fma_f32 v[144:145], v[92:93], v[86:87], v[144:145] op_sel_hi:[1,0,1]
	v_pk_fma_f32 v[146:147], v[92:93], v[86:87], v[146:147] op_sel:[0,1,0]
	v_add_f32_dpp v150, v150, v150 quad_perm:[1,0,3,2] row_mask:0xf bank_mask:0xf bound_ctrl:1
	v_pk_fma_f32 v[64:65], v[106:107], v[80:81], v[110:111] op_sel_hi:[1,0,1]
	v_pk_fma_f32 v[66:67], v[106:107], v[80:81], v[112:113] op_sel:[0,1,0]
	v_add_f32_dpp v150, v150, v150 quad_perm:[2,3,0,1] row_mask:0xf bank_mask:0xf bound_ctrl:1
	v_pk_fma_f32 v[68:69], v[106:107], v[82:83], v[144:145] op_sel_hi:[1,0,1]
	v_pk_fma_f32 v[70:71], v[106:107], v[82:83], v[146:147] op_sel:[0,1,0]
	s_mov_b64 exec, s[34:35]
	ds_write_b32 v178, v150 offset:2560
	s_mov_b64 exec, -1
	s_waitcnt lgkmcnt(1)
; #define SC_GET(X, t) do { const float* p = rec + (t) * 320; w##X = *(const f32x4*)p; a##X = *(const f32x4*)(p + 4); b##X = *(const f32x4*)(p + 8); k##X = *(const f32x4*)(p + 12); q##X = *(const f32x4*)(p + 16); \
;                 v##X = *(const f32x4*)(VVa + (t) * 64); } while (0)
; DI void scan_phase(unsigned char* lds, const Ctx& a, const Op& d, const int variant) {
;     ...
;                 SC_GET(A, 0);
; #pragma unroll 2
;                 for (int t = 0; t < SC_T; t += 2) {
;                     SC_GET(B, t + 1);
;                     SC_STEP(A, t);
;                     if (t + 2 < SC_T) SC_GET(A, t + 2);
;                     SC_STEP(B, t + 1);
;                 }
	ds_read_b128 v[72:75], v175 offset:29440
	ds_read_b128 v[76:79], v175 offset:29456
	ds_read_b128 v[80:83], v175 offset:29472
	ds_read_b128 v[84:87], v175 offset:29488
	ds_read_b128 v[88:91], v175 offset:29504
	ds_read_b128 v[92:95], v123 offset:46848
	v_pk_mul_f32 v[106:107], v[64:65], v[44:45] op_sel_hi:[1,0]
	v_pk_mul_f32 v[108:109], v[64:65], v[56:57] op_sel_hi:[1,0]
	v_pk_fma_f32 v[106:107], v[66:67], v[44:45], v[106:107] op_sel:[0,1,0]
	v_pk_fma_f32 v[108:109], v[66:67], v[56:57], v[108:109] op_sel:[0,1,0]
	v_pk_fma_f32 v[106:107], v[68:69], v[46:47], v[106:107] op_sel_hi:[1,0,1]
	v_pk_fma_f32 v[108:109], v[68:69], v[58:59], v[108:109] op_sel_hi:[1,0,1]
	v_pk_fma_f32 v[106:107], v[70:71], v[46:47], v[106:107] op_sel:[0,1,0]
	v_pk_fma_f32 v[108:109], v[70:71], v[58:59], v[108:109] op_sel:[0,1,0]
	v_pk_mul_f32 v[110:111], v[64:65], v[40:41] op_sel_hi:[1,0]
	v_add_f32_dpp v106, v106, v106 quad_perm:[1,0,3,2] row_mask:0xf bank_mask:0xf bound_ctrl:1
	v_add_f32_dpp v107, v107, v107 quad_perm:[1,0,3,2] row_mask:0xf bank_mask:0xf bound_ctrl:1
	v_pk_fma_f32 v[108:109], v[62:63], v[176:177], v[108:109]
	v_pk_mul_f32 v[112:113], v[66:67], v[40:41] op_sel:[0,1]
	v_add_f32_dpp v106, v106, v106 quad_perm:[2,3,0,1] row_mask:0xf bank_mask:0xf bound_ctrl:1
	v_add_f32_dpp v107, v107, v107 quad_perm:[2,3,0,1] row_mask:0xf bank_mask:0xf bound_ctrl:1
	v_add_f32_dpp v148, v108, v108 row_half_mirror row_mask:0xf bank_mask:0xf bound_ctrl:1
	v_add_f32_dpp v148, v109, v109 row_half_mirror row_mask:0xf bank_mask:0xa
	v_add_f32_dpp v106, v106, v106 row_half_mirror row_mask:0xf bank_mask:0xf bound_ctrl:1
	v_add_f32_dpp v107, v107, v107 row_half_mirror row_mask:0xf bank_mask:0xf bound_ctrl:1
	v_pk_mul_f32 v[144:145], v[68:69], v[42:43] op_sel_hi:[1,0]
	v_pk_mul_f32 v[146:147], v[70:71], v[42:43] op_sel:[0,1]
	v_add_f32_dpp v106, v106, v106 row_mirror row_mask:0xf bank_mask:0xf bound_ctrl:1
	v_add_f32_dpp v107, v107, v107 row_mirror row_mask:0xf bank_mask:0xf bound_ctrl:1
	v_pk_fma_f32 v[110:111], v[60:61], v[52:53], v[110:111] op_sel_hi:[1,0,1]
	v_pk_fma_f32 v[112:113], v[60:61], v[52:53], v[112:113] op_sel:[0,1,0]
	v_pk_fma_f32 v[144:145], v[60:61], v[54:55], v[144:145] op_sel_hi:[1,0,1]
	v_pk_fma_f32 v[146:147], v[60:61], v[54:55], v[146:147] op_sel:[0,1,0]
	v_pk_fma_f32 v[64:65], v[106:107], v[48:49], v[110:111] op_sel_hi:[1,0,1]
	v_pk_fma_f32 v[66:67], v[106:107], v[48:49], v[112:113] op_sel:[0,1,0]
	v_pk_fma_f32 v[68:69], v[106:107], v[50:51], v[144:145] op_sel_hi:[1,0,1]
	v_pk_fma_f32 v[70:71], v[106:107], v[50:51], v[146:147] op_sel:[0,1,0]
	s_waitcnt lgkmcnt(0)
	ds_read_b128 v[40:43], v175 offset:30720
	ds_read_b128 v[44:47], v175 offset:30736
	ds_read_b128 v[48:51], v175 offset:30752
	ds_read_b128 v[52:55], v175 offset:30768
	ds_read_b128 v[56:59], v175 offset:30784
	ds_read_b128 v[60:63], v123 offset:47104
	v_pk_mul_f32 v[106:107], v[64:65], v[76:77] op_sel_hi:[1,0]
	v_pk_mul_f32 v[108:109], v[64:65], v[88:89] op_sel_hi:[1,0]
	v_pk_fma_f32 v[106:107], v[66:67], v[76:77], v[106:107] op_sel:[0,1,0]
	v_pk_fma_f32 v[108:109], v[66:67], v[88:89], v[108:109] op_sel:[0,1,0]
	v_pk_fma_f32 v[106:107], v[68:69], v[78:79], v[106:107] op_sel_hi:[1,0,1]
	v_pk_fma_f32 v[108:109], v[68:69], v[90:91], v[108:109] op_sel_hi:[1,0,1]
	v_pk_fma_f32 v[106:107], v[70:71], v[78:79], v[106:107] op_sel:[0,1,0]
	v_pk_fma_f32 v[108:109], v[70:71], v[90:91], v[108:109] op_sel:[0,1,0]
	v_pk_mul_f32 v[110:111], v[64:65], v[72:73] op_sel_hi:[1,0]
	v_add_f32_dpp v106, v106, v106 quad_perm:[1,0,3,2] row_mask:0xf bank_mask:0xf bound_ctrl:1
	v_add_f32_dpp v107, v107, v107 quad_perm:[1,0,3,2] row_mask:0xf bank_mask:0xf bound_ctrl:1
	v_pk_fma_f32 v[108:109], v[94:95], v[176:177], v[108:109]
	v_pk_mul_f32 v[112:113], v[66:67], v[72:73] op_sel:[0,1]
	v_add_f32_dpp v106, v106, v106 quad_perm:[2,3,0,1] row_mask:0xf bank_mask:0xf bound_ctrl:1
	v_add_f32_dpp v107, v107, v107 quad_perm:[2,3,0,1] row_mask:0xf bank_mask:0xf bound_ctrl:1
	v_add_f32_dpp v149, v108, v108 row_half_mirror row_mask:0xf bank_mask:0xf bound_ctrl:1
	v_add_f32_dpp v149, v109, v109 row_half_mirror row_mask:0xf bank_mask:0xa
	v_add_f32_dpp v106, v106, v106 row_half_mirror row_mask:0xf bank_mask:0xf bound_ctrl:1
	v_add_f32_dpp v107, v107, v107 row_half_mirror row_mask:0xf bank_mask:0xf bound_ctrl:1
	v_pk_mul_f32 v[144:145], v[68:69], v[74:75] op_sel_hi:[1,0]
	v_pk_mul_f32 v[146:147], v[70:71], v[74:75] op_sel:[0,1]
	v_add_f32_dpp v150, v148, v148 row_ror:8 row_mask:0xf bank_mask:0xf bound_ctrl:1
	v_add_f32_dpp v150, v149, v149 row_ror:8 row_mask:0xf bank_mask:0xc
	v_add_f32_dpp v106, v106, v106 row_mirror row_mask:0xf bank_mask:0xf bound_ctrl:1
	v_add_f32_dpp v107, v107, v107 row_mirror row_mask:0xf bank_mask:0xf bound_ctrl:1
	v_pk_fma_f32 v[110:111], v[92:93], v[84:85], v[110:111] op_sel_hi:[1,0,1]
	v_pk_fma_f32 v[112:113], v[92:93], v[84:85], v[112:113] op_sel:[0,1,0]
	v_pk_fma_f32 v[144:145], v[92:93], v[86:87], v[144:145] op_sel_hi:[1,0,1]
	v_pk_fma_f32 v[146:147], v[92:93], v[86:87], v[146:147] op_sel:[0,1,0]
	v_add_f32_dpp v150, v150, v150 quad_perm:[1,0,3,2] row_mask:0xf bank_mask:0xf bound_ctrl:1
	v_pk_fma_f32 v[64:65], v[106:107], v[80:81], v[110:111] op_sel_hi:[1,0,1]
	v_pk_fma_f32 v[66:67], v[106:107], v[80:81], v[112:113] op_sel:[0,1,0]
	v_add_f32_dpp v150, v150, v150 quad_perm:[2,3,0,1] row_mask:0xf bank_mask:0xf bound_ctrl:1
	v_pk_fma_f32 v[68:69], v[106:107], v[82:83], v[144:145] op_sel_hi:[1,0,1]
	v_pk_fma_f32 v[70:71], v[106:107], v[82:83], v[146:147] op_sel:[0,1,0]
	s_mov_b64 exec, s[34:35]
	ds_write_b32 v178, v150 offset:2816
	s_mov_b64 exec, -1
	s_waitcnt lgkmcnt(1)
; #define SC_GET(X, t) do { const float* p = rec + (t) * 320; w##X = *(const f32x4*)p; a##X = *(const f32x4*)(p + 4); b##X = *(const f32x4*)(p + 8); k##X = *(const f32x4*)(p + 12); q##X = *(const f32x4*)(p + 16); \
;                 v##X = *(const f32x4*)(VVa + (t) * 64); } while (0)
; DI void scan_phase(unsigned char* lds, const Ctx& a, const Op& d, const int variant) {
;     ...
;                 SC_GET(A, 0);
; #pragma unroll 2
;                 for (int t = 0; t < SC_T; t += 2) {
;                     SC_GET(B, t + 1);
;                     SC_STEP(A, t);
;                     if (t + 2 < SC_T) SC_GET(A, t + 2);
;                     SC_STEP(B, t + 1);
;                 }
	ds_read_b128 v[72:75], v175 offset:32000
	ds_read_b128 v[76:79], v175 offset:32016
	ds_read_b128 v[80:83], v175 offset:32032
	ds_read_b128 v[84:87], v175 offset:32048
	ds_read_b128 v[88:91], v175 offset:32064
	ds_read_b128 v[92:95], v123 offset:47360
	v_pk_mul_f32 v[106:107], v[64:65], v[44:45] op_sel_hi:[1,0]
	v_pk_mul_f32 v[108:109], v[64:65], v[56:57] op_sel_hi:[1,0]
	v_pk_fma_f32 v[106:107], v[66:67], v[44:45], v[106:107] op_sel:[0,1,0]
	v_pk_fma_f32 v[108:109], v[66:67], v[56:57], v[108:109] op_sel:[0,1,0]
	v_pk_fma_f32 v[106:107], v[68:69], v[46:47], v[106:107] op_sel_hi:[1,0,1]
	v_pk_fma_f32 v[108:109], v[68:69], v[58:59], v[108:109] op_sel_hi:[1,0,1]
	v_pk_fma_f32 v[106:107], v[70:71], v[46:47], v[106:107] op_sel:[0,1,0]
	v_pk_fma_f32 v[108:109], v[70:71], v[58:59], v[108:109] op_sel:[0,1,0]
	v_pk_mul_f32 v[110:111], v[64:65], v[40:41] op_sel_hi:[1,0]
	v_add_f32_dpp v106, v106, v106 quad_perm:[1,0,3,2] row_mask:0xf bank_mask:0xf bound_ctrl:1
	v_add_f32_dpp v107, v107, v107 quad_perm:[1,0,3,2] row_mask:0xf bank_mask:0xf bound_ctrl:1
	v_pk_fma_f32 v[108:109], v[62:63], v[176:177], v[108:109]
	v_pk_mul_f32 v[112:113], v[66:67], v[40:41] op_sel:[0,1]
	v_add_f32_dpp v106, v106, v106 quad_perm:[2,3,0,1] row_mask:0xf bank_mask:0xf bound_ctrl:1
	v_add_f32_dpp v107, v107, v107 quad_perm:[2,3,0,1] row_mask:0xf bank_mask:0xf bound_ctrl:1
	v_add_f32_dpp v148, v108, v108 row_half_mirror row_mask:0xf bank_mask:0xf bound_ctrl:1
	v_add_f32_dpp v148, v109, v109 row_half_mirror row_mask:0xf bank_mask:0xa
	v_add_f32_dpp v106, v106, v106 row_half_mirror row_mask:0xf bank_mask:0xf bound_ctrl:1
	v_add_f32_dpp v107, v107, v107 row_half_mirror row_mask:0xf bank_mask:0xf bound_ctrl:1
	v_pk_mul_f32 v[144:145], v[68:69], v[42:43] op_sel_hi:[1,0]
	v_pk_mul_f32 v[146:147], v[70:71], v[42:43] op_sel:[0,1]
	v_add_f32_dpp v106, v106, v106 row_mirror row_mask:0xf bank_mask:0xf bound_ctrl:1
	v_add_f32_dpp v107, v107, v107 row_mirror row_mask:0xf bank_mask:0xf bound_ctrl:1
	v_pk_fma_f32 v[110:111], v[60:61], v[52:53], v[110:111] op_sel_hi:[1,0,1]
	v_pk_fma_f32 v[112:113], v[60:61], v[52:53], v[112:113] op_sel:[0,1,0]
	v_pk_fma_f32 v[144:145], v[60:61], v[54:55], v[144:145] op_sel_hi:[1,0,1]
	v_pk_fma_f32 v[146:147], v[60:61], v[54:55], v[146:147] op_sel:[0,1,0]
	v_pk_fma_f32 v[64:65], v[106:107], v[48:49], v[110:111] op_sel_hi:[1,0,1]
	v_pk_fma_f32 v[66:67], v[106:107], v[48:49], v[112:113] op_sel:[0,1,0]
	v_pk_fma_f32 v[68:69], v[106:107], v[50:51], v[144:145] op_sel_hi:[1,0,1]
	v_pk_fma_f32 v[70:71], v[106:107], v[50:51], v[146:147] op_sel:[0,1,0]
	s_waitcnt lgkmcnt(0)
	ds_read_b128 v[40:43], v175 offset:33280
	ds_read_b128 v[44:47], v175 offset:33296
	ds_read_b128 v[48:51], v175 offset:33312
	ds_read_b128 v[52:55], v175 offset:33328
	ds_read_b128 v[56:59], v175 offset:33344
	ds_read_b128 v[60:63], v123 offset:47616
	v_pk_mul_f32 v[106:107], v[64:65], v[76:77] op_sel_hi:[1,0]
	v_pk_mul_f32 v[108:109], v[64:65], v[88:89] op_sel_hi:[1,0]
	v_pk_fma_f32 v[106:107], v[66:67], v[76:77], v[106:107] op_sel:[0,1,0]
	v_pk_fma_f32 v[108:109], v[66:67], v[88:89], v[108:109] op_sel:[0,1,0]
	v_pk_fma_f32 v[106:107], v[68:69], v[78:79], v[106:107] op_sel_hi:[1,0,1]
	v_pk_fma_f32 v[108:109], v[68:69], v[90:91], v[108:109] op_sel_hi:[1,0,1]
	v_pk_fma_f32 v[106:107], v[70:71], v[78:79], v[106:107] op_sel:[0,1,0]
	v_pk_fma_f32 v[108:109], v[70:71], v[90:91], v[108:109] op_sel:[0,1,0]
	v_pk_mul_f32 v[110:111], v[64:65], v[72:73] op_sel_hi:[1,0]
	v_add_f32_dpp v106, v106, v106 quad_perm:[1,0,3,2] row_mask:0xf bank_mask:0xf bound_ctrl:1
	v_add_f32_dpp v107, v107, v107 quad_perm:[1,0,3,2] row_mask:0xf bank_mask:0xf bound_ctrl:1
	v_pk_fma_f32 v[108:109], v[94:95], v[176:177], v[108:109]
	v_pk_mul_f32 v[112:113], v[66:67], v[72:73] op_sel:[0,1]
	v_add_f32_dpp v106, v106, v106 quad_perm:[2,3,0,1] row_mask:0xf bank_mask:0xf bound_ctrl:1
	v_add_f32_dpp v107, v107, v107 quad_perm:[2,3,0,1] row_mask:0xf bank_mask:0xf bound_ctrl:1
	v_add_f32_dpp v149, v108, v108 row_half_mirror row_mask:0xf bank_mask:0xf bound_ctrl:1
	v_add_f32_dpp v149, v109, v109 row_half_mirror row_mask:0xf bank_mask:0xa
	v_add_f32_dpp v106, v106, v106 row_half_mirror row_mask:0xf bank_mask:0xf bound_ctrl:1
	v_add_f32_dpp v107, v107, v107 row_half_mirror row_mask:0xf bank_mask:0xf bound_ctrl:1
	v_pk_mul_f32 v[144:145], v[68:69], v[74:75] op_sel_hi:[1,0]
	v_pk_mul_f32 v[146:147], v[70:71], v[74:75] op_sel:[0,1]
	v_add_f32_dpp v150, v148, v148 row_ror:8 row_mask:0xf bank_mask:0xf bound_ctrl:1
	v_add_f32_dpp v150, v149, v149 row_ror:8 row_mask:0xf bank_mask:0xc
	v_add_f32_dpp v106, v106, v106 row_mirror row_mask:0xf bank_mask:0xf bound_ctrl:1
	v_add_f32_dpp v107, v107, v107 row_mirror row_mask:0xf bank_mask:0xf bound_ctrl:1
	v_pk_fma_f32 v[110:111], v[92:93], v[84:85], v[110:111] op_sel_hi:[1,0,1]
	v_pk_fma_f32 v[112:113], v[92:93], v[84:85], v[112:113] op_sel:[0,1,0]
	v_pk_fma_f32 v[144:145], v[92:93], v[86:87], v[144:145] op_sel_hi:[1,0,1]
	v_pk_fma_f32 v[146:147], v[92:93], v[86:87], v[146:147] op_sel:[0,1,0]
	v_add_f32_dpp v150, v150, v150 quad_perm:[1,0,3,2] row_mask:0xf bank_mask:0xf bound_ctrl:1
	v_pk_fma_f32 v[64:65], v[106:107], v[80:81], v[110:111] op_sel_hi:[1,0,1]
	v_pk_fma_f32 v[66:67], v[106:107], v[80:81], v[112:113] op_sel:[0,1,0]
	v_add_f32_dpp v150, v150, v150 quad_perm:[2,3,0,1] row_mask:0xf bank_mask:0xf bound_ctrl:1
	v_pk_fma_f32 v[68:69], v[106:107], v[82:83], v[144:145] op_sel_hi:[1,0,1]
	v_pk_fma_f32 v[70:71], v[106:107], v[82:83], v[146:147] op_sel:[0,1,0]
	s_mov_b64 exec, s[34:35]
	ds_write_b32 v178, v150 offset:3072
	s_mov_b64 exec, -1
	s_waitcnt lgkmcnt(1)
; #define SC_GET(X, t) do { const float* p = rec + (t) * 320; w##X = *(const f32x4*)p; a##X = *(const f32x4*)(p + 4); b##X = *(const f32x4*)(p + 8); k##X = *(const f32x4*)(p + 12); q##X = *(const f32x4*)(p + 16); \
;                 v##X = *(const f32x4*)(VVa + (t) * 64); } while (0)
; DI void scan_phase(unsigned char* lds, const Ctx& a, const Op& d, const int variant) {
;     ...
;                 SC_GET(A, 0);
; #pragma unroll 2
;                 for (int t = 0; t < SC_T; t += 2) {
;                     SC_GET(B, t + 1);
;                     SC_STEP(A, t);
;                     if (t + 2 < SC_T) SC_GET(A, t + 2);
;                     SC_STEP(B, t + 1);
;                 }
	ds_read_b128 v[72:75], v175 offset:34560
	ds_read_b128 v[76:79], v175 offset:34576
	ds_read_b128 v[80:83], v175 offset:34592
	ds_read_b128 v[84:87], v175 offset:34608
	ds_read_b128 v[88:91], v175 offset:34624
	ds_read_b128 v[92:95], v123 offset:47872
	v_pk_mul_f32 v[106:107], v[64:65], v[44:45] op_sel_hi:[1,0]
	v_pk_mul_f32 v[108:109], v[64:65], v[56:57] op_sel_hi:[1,0]
	v_pk_fma_f32 v[106:107], v[66:67], v[44:45], v[106:107] op_sel:[0,1,0]
	v_pk_fma_f32 v[108:109], v[66:67], v[56:57], v[108:109] op_sel:[0,1,0]
	v_pk_fma_f32 v[106:107], v[68:69], v[46:47], v[106:107] op_sel_hi:[1,0,1]
	v_pk_fma_f32 v[108:109], v[68:69], v[58:59], v[108:109] op_sel_hi:[1,0,1]
	v_pk_fma_f32 v[106:107], v[70:71], v[46:47], v[106:107] op_sel:[0,1,0]
	v_pk_fma_f32 v[108:109], v[70:71], v[58:59], v[108:109] op_sel:[0,1,0]
	v_pk_mul_f32 v[110:111], v[64:65], v[40:41] op_sel_hi:[1,0]
	v_add_f32_dpp v106, v106, v106 quad_perm:[1,0,3,2] row_mask:0xf bank_mask:0xf bound_ctrl:1
	v_add_f32_dpp v107, v107, v107 quad_perm:[1,0,3,2] row_mask:0xf bank_mask:0xf bound_ctrl:1
	v_pk_fma_f32 v[108:109], v[62:63], v[176:177], v[108:109]
	v_pk_mul_f32 v[112:113], v[66:67], v[40:41] op_sel:[0,1]
	v_add_f32_dpp v106, v106, v106 quad_perm:[2,3,0,1] row_mask:0xf bank_mask:0xf bound_ctrl:1
	v_add_f32_dpp v107, v107, v107 quad_perm:[2,3,0,1] row_mask:0xf bank_mask:0xf bound_ctrl:1
	v_add_f32_dpp v148, v108, v108 row_half_mirror row_mask:0xf bank_mask:0xf bound_ctrl:1
	v_add_f32_dpp v148, v109, v109 row_half_mirror row_mask:0xf bank_mask:0xa
	v_add_f32_dpp v106, v106, v106 row_half_mirror row_mask:0xf bank_mask:0xf bound_ctrl:1
	v_add_f32_dpp v107, v107, v107 row_half_mirror row_mask:0xf bank_mask:0xf bound_ctrl:1
	v_pk_mul_f32 v[144:145], v[68:69], v[42:43] op_sel_hi:[1,0]
	v_pk_mul_f32 v[146:147], v[70:71], v[42:43] op_sel:[0,1]
	v_add_f32_dpp v106, v106, v106 row_mirror row_mask:0xf bank_mask:0xf bound_ctrl:1
	v_add_f32_dpp v107, v107, v107 row_mirror row_mask:0xf bank_mask:0xf bound_ctrl:1
	v_pk_fma_f32 v[110:111], v[60:61], v[52:53], v[110:111] op_sel_hi:[1,0,1]
	v_pk_fma_f32 v[112:113], v[60:61], v[52:53], v[112:113] op_sel:[0,1,0]
	v_pk_fma_f32 v[144:145], v[60:61], v[54:55], v[144:145] op_sel_hi:[1,0,1]
	v_pk_fma_f32 v[146:147], v[60:61], v[54:55], v[146:147] op_sel:[0,1,0]
	v_pk_fma_f32 v[64:65], v[106:107], v[48:49], v[110:111] op_sel_hi:[1,0,1]
	v_pk_fma_f32 v[66:67], v[106:107], v[48:49], v[112:113] op_sel:[0,1,0]
	v_pk_fma_f32 v[68:69], v[106:107], v[50:51], v[144:145] op_sel_hi:[1,0,1]
	v_pk_fma_f32 v[70:71], v[106:107], v[50:51], v[146:147] op_sel:[0,1,0]
	s_waitcnt lgkmcnt(0)
	ds_read_b128 v[40:43], v175 offset:35840
	ds_read_b128 v[44:47], v175 offset:35856
	ds_read_b128 v[48:51], v175 offset:35872
	ds_read_b128 v[52:55], v175 offset:35888
	ds_read_b128 v[56:59], v175 offset:35904
	ds_read_b128 v[60:63], v123 offset:48128
	v_pk_mul_f32 v[106:107], v[64:65], v[76:77] op_sel_hi:[1,0]
	v_pk_mul_f32 v[108:109], v[64:65], v[88:89] op_sel_hi:[1,0]
	v_pk_fma_f32 v[106:107], v[66:67], v[76:77], v[106:107] op_sel:[0,1,0]
	v_pk_fma_f32 v[108:109], v[66:67], v[88:89], v[108:109] op_sel:[0,1,0]
	v_pk_fma_f32 v[106:107], v[68:69], v[78:79], v[106:107] op_sel_hi:[1,0,1]
	v_pk_fma_f32 v[108:109], v[68:69], v[90:91], v[108:109] op_sel_hi:[1,0,1]
	v_pk_fma_f32 v[106:107], v[70:71], v[78:79], v[106:107] op_sel:[0,1,0]
	v_pk_fma_f32 v[108:109], v[70:71], v[90:91], v[108:109] op_sel:[0,1,0]
	v_pk_mul_f32 v[110:111], v[64:65], v[72:73] op_sel_hi:[1,0]
	v_add_f32_dpp v106, v106, v106 quad_perm:[1,0,3,2] row_mask:0xf bank_mask:0xf bound_ctrl:1
	v_add_f32_dpp v107, v107, v107 quad_perm:[1,0,3,2] row_mask:0xf bank_mask:0xf bound_ctrl:1
	v_pk_fma_f32 v[108:109], v[94:95], v[176:177], v[108:109]
	v_pk_mul_f32 v[112:113], v[66:67], v[72:73] op_sel:[0,1]
	v_add_f32_dpp v106, v106, v106 quad_perm:[2,3,0,1] row_mask:0xf bank_mask:0xf bound_ctrl:1
	v_add_f32_dpp v107, v107, v107 quad_perm:[2,3,0,1] row_mask:0xf bank_mask:0xf bound_ctrl:1
	v_add_f32_dpp v149, v108, v108 row_half_mirror row_mask:0xf bank_mask:0xf bound_ctrl:1
	v_add_f32_dpp v149, v109, v109 row_half_mirror row_mask:0xf bank_mask:0xa
	v_add_f32_dpp v106, v106, v106 row_half_mirror row_mask:0xf bank_mask:0xf bound_ctrl:1
	v_add_f32_dpp v107, v107, v107 row_half_mirror row_mask:0xf bank_mask:0xf bound_ctrl:1
	v_pk_mul_f32 v[144:145], v[68:69], v[74:75] op_sel_hi:[1,0]
	v_pk_mul_f32 v[146:147], v[70:71], v[74:75] op_sel:[0,1]
	v_add_f32_dpp v150, v148, v148 row_ror:8 row_mask:0xf bank_mask:0xf bound_ctrl:1
	v_add_f32_dpp v150, v149, v149 row_ror:8 row_mask:0xf bank_mask:0xc
	v_add_f32_dpp v106, v106, v106 row_mirror row_mask:0xf bank_mask:0xf bound_ctrl:1
	v_add_f32_dpp v107, v107, v107 row_mirror row_mask:0xf bank_mask:0xf bound_ctrl:1
	v_pk_fma_f32 v[110:111], v[92:93], v[84:85], v[110:111] op_sel_hi:[1,0,1]
	v_pk_fma_f32 v[112:113], v[92:93], v[84:85], v[112:113] op_sel:[0,1,0]
	v_pk_fma_f32 v[144:145], v[92:93], v[86:87], v[144:145] op_sel_hi:[1,0,1]
	v_pk_fma_f32 v[146:147], v[92:93], v[86:87], v[146:147] op_sel:[0,1,0]
	v_add_f32_dpp v150, v150, v150 quad_perm:[1,0,3,2] row_mask:0xf bank_mask:0xf bound_ctrl:1
	v_pk_fma_f32 v[64:65], v[106:107], v[80:81], v[110:111] op_sel_hi:[1,0,1]
	v_pk_fma_f32 v[66:67], v[106:107], v[80:81], v[112:113] op_sel:[0,1,0]
	v_add_f32_dpp v150, v150, v150 quad_perm:[2,3,0,1] row_mask:0xf bank_mask:0xf bound_ctrl:1
	v_pk_fma_f32 v[68:69], v[106:107], v[82:83], v[144:145] op_sel_hi:[1,0,1]
	v_pk_fma_f32 v[70:71], v[106:107], v[82:83], v[146:147] op_sel:[0,1,0]
	s_mov_b64 exec, s[34:35]
	ds_write_b32 v178, v150 offset:3328
	s_mov_b64 exec, -1
	s_waitcnt lgkmcnt(1)
; #define SC_GET(X, t) do { const float* p = rec + (t) * 320; w##X = *(const f32x4*)p; a##X = *(const f32x4*)(p + 4); b##X = *(const f32x4*)(p + 8); k##X = *(const f32x4*)(p + 12); q##X = *(const f32x4*)(p + 16); \
;                 v##X = *(const f32x4*)(VVa + (t) * 64); } while (0)
; DI void scan_phase(unsigned char* lds, const Ctx& a, const Op& d, const int variant) {
;     ...
;                 SC_GET(A, 0);
; #pragma unroll 2
;                 for (int t = 0; t < SC_T; t += 2) {
;                     SC_GET(B, t + 1);
;                     SC_STEP(A, t);
;                     if (t + 2 < SC_T) SC_GET(A, t + 2);
;                     SC_STEP(B, t + 1);
;                 }
	ds_read_b128 v[72:75], v175 offset:37120
	ds_read_b128 v[76:79], v175 offset:37136
	ds_read_b128 v[80:83], v175 offset:37152
	ds_read_b128 v[84:87], v175 offset:37168
	ds_read_b128 v[88:91], v175 offset:37184
	ds_read_b128 v[92:95], v123 offset:48384
	v_pk_mul_f32 v[106:107], v[64:65], v[44:45] op_sel_hi:[1,0]
	v_pk_mul_f32 v[108:109], v[64:65], v[56:57] op_sel_hi:[1,0]
	v_pk_fma_f32 v[106:107], v[66:67], v[44:45], v[106:107] op_sel:[0,1,0]
	v_pk_fma_f32 v[108:109], v[66:67], v[56:57], v[108:109] op_sel:[0,1,0]
	v_pk_fma_f32 v[106:107], v[68:69], v[46:47], v[106:107] op_sel_hi:[1,0,1]
	v_pk_fma_f32 v[108:109], v[68:69], v[58:59], v[108:109] op_sel_hi:[1,0,1]
	v_pk_fma_f32 v[106:107], v[70:71], v[46:47], v[106:107] op_sel:[0,1,0]
	v_pk_fma_f32 v[108:109], v[70:71], v[58:59], v[108:109] op_sel:[0,1,0]
	v_pk_mul_f32 v[110:111], v[64:65], v[40:41] op_sel_hi:[1,0]
	v_add_f32_dpp v106, v106, v106 quad_perm:[1,0,3,2] row_mask:0xf bank_mask:0xf bound_ctrl:1
	v_add_f32_dpp v107, v107, v107 quad_perm:[1,0,3,2] row_mask:0xf bank_mask:0xf bound_ctrl:1
	v_pk_fma_f32 v[108:109], v[62:63], v[176:177], v[108:109]
	v_pk_mul_f32 v[112:113], v[66:67], v[40:41] op_sel:[0,1]
	v_add_f32_dpp v106, v106, v106 quad_perm:[2,3,0,1] row_mask:0xf bank_mask:0xf bound_ctrl:1
	v_add_f32_dpp v107, v107, v107 quad_perm:[2,3,0,1] row_mask:0xf bank_mask:0xf bound_ctrl:1
	v_add_f32_dpp v148, v108, v108 row_half_mirror row_mask:0xf bank_mask:0xf bound_ctrl:1
	v_add_f32_dpp v148, v109, v109 row_half_mirror row_mask:0xf bank_mask:0xa
	v_add_f32_dpp v106, v106, v106 row_half_mirror row_mask:0xf bank_mask:0xf bound_ctrl:1
	v_add_f32_dpp v107, v107, v107 row_half_mirror row_mask:0xf bank_mask:0xf bound_ctrl:1
	v_pk_mul_f32 v[144:145], v[68:69], v[42:43] op_sel_hi:[1,0]
	v_pk_mul_f32 v[146:147], v[70:71], v[42:43] op_sel:[0,1]
	v_add_f32_dpp v106, v106, v106 row_mirror row_mask:0xf bank_mask:0xf bound_ctrl:1
	v_add_f32_dpp v107, v107, v107 row_mirror row_mask:0xf bank_mask:0xf bound_ctrl:1
	v_pk_fma_f32 v[110:111], v[60:61], v[52:53], v[110:111] op_sel_hi:[1,0,1]
	v_pk_fma_f32 v[112:113], v[60:61], v[52:53], v[112:113] op_sel:[0,1,0]
	v_pk_fma_f32 v[144:145], v[60:61], v[54:55], v[144:145] op_sel_hi:[1,0,1]
	v_pk_fma_f32 v[146:147], v[60:61], v[54:55], v[146:147] op_sel:[0,1,0]
	v_pk_fma_f32 v[64:65], v[106:107], v[48:49], v[110:111] op_sel_hi:[1,0,1]
	v_pk_fma_f32 v[66:67], v[106:107], v[48:49], v[112:113] op_sel:[0,1,0]
	v_pk_fma_f32 v[68:69], v[106:107], v[50:51], v[144:145] op_sel_hi:[1,0,1]
	v_pk_fma_f32 v[70:71], v[106:107], v[50:51], v[146:147] op_sel:[0,1,0]
	s_waitcnt lgkmcnt(0)
	ds_read_b128 v[40:43], v175 offset:38400
	ds_read_b128 v[44:47], v175 offset:38416
	ds_read_b128 v[48:51], v175 offset:38432
	ds_read_b128 v[52:55], v175 offset:38448
	ds_read_b128 v[56:59], v175 offset:38464
	ds_read_b128 v[60:63], v123 offset:48640
	v_pk_mul_f32 v[106:107], v[64:65], v[76:77] op_sel_hi:[1,0]
	v_pk_mul_f32 v[108:109], v[64:65], v[88:89] op_sel_hi:[1,0]
	v_pk_fma_f32 v[106:107], v[66:67], v[76:77], v[106:107] op_sel:[0,1,0]
	v_pk_fma_f32 v[108:109], v[66:67], v[88:89], v[108:109] op_sel:[0,1,0]
	v_pk_fma_f32 v[106:107], v[68:69], v[78:79], v[106:107] op_sel_hi:[1,0,1]
	v_pk_fma_f32 v[108:109], v[68:69], v[90:91], v[108:109] op_sel_hi:[1,0,1]
	v_pk_fma_f32 v[106:107], v[70:71], v[78:79], v[106:107] op_sel:[0,1,0]
	v_pk_fma_f32 v[108:109], v[70:71], v[90:91], v[108:109] op_sel:[0,1,0]
	v_pk_mul_f32 v[110:111], v[64:65], v[72:73] op_sel_hi:[1,0]
	v_add_f32_dpp v106, v106, v106 quad_perm:[1,0,3,2] row_mask:0xf bank_mask:0xf bound_ctrl:1
	v_add_f32_dpp v107, v107, v107 quad_perm:[1,0,3,2] row_mask:0xf bank_mask:0xf bound_ctrl:1
	v_pk_fma_f32 v[108:109], v[94:95], v[176:177], v[108:109]
	v_pk_mul_f32 v[112:113], v[66:67], v[72:73] op_sel:[0,1]
	v_add_f32_dpp v106, v106, v106 quad_perm:[2,3,0,1] row_mask:0xf bank_mask:0xf bound_ctrl:1
	v_add_f32_dpp v107, v107, v107 quad_perm:[2,3,0,1] row_mask:0xf bank_mask:0xf bound_ctrl:1
	v_add_f32_dpp v149, v108, v108 row_half_mirror row_mask:0xf bank_mask:0xf bound_ctrl:1
	v_add_f32_dpp v149, v109, v109 row_half_mirror row_mask:0xf bank_mask:0xa
	v_add_f32_dpp v106, v106, v106 row_half_mirror row_mask:0xf bank_mask:0xf bound_ctrl:1
	v_add_f32_dpp v107, v107, v107 row_half_mirror row_mask:0xf bank_mask:0xf bound_ctrl:1
	v_pk_mul_f32 v[144:145], v[68:69], v[74:75] op_sel_hi:[1,0]
	v_pk_mul_f32 v[146:147], v[70:71], v[74:75] op_sel:[0,1]
	v_add_f32_dpp v150, v148, v148 row_ror:8 row_mask:0xf bank_mask:0xf bound_ctrl:1
	v_add_f32_dpp v150, v149, v149 row_ror:8 row_mask:0xf bank_mask:0xc
	v_add_f32_dpp v106, v106, v106 row_mirror row_mask:0xf bank_mask:0xf bound_ctrl:1
	v_add_f32_dpp v107, v107, v107 row_mirror row_mask:0xf bank_mask:0xf bound_ctrl:1
	v_pk_fma_f32 v[110:111], v[92:93], v[84:85], v[110:111] op_sel_hi:[1,0,1]
	v_pk_fma_f32 v[112:113], v[92:93], v[84:85], v[112:113] op_sel:[0,1,0]
	v_pk_fma_f32 v[144:145], v[92:93], v[86:87], v[144:145] op_sel_hi:[1,0,1]
	v_pk_fma_f32 v[146:147], v[92:93], v[86:87], v[146:147] op_sel:[0,1,0]
	v_add_f32_dpp v150, v150, v150 quad_perm:[1,0,3,2] row_mask:0xf bank_mask:0xf bound_ctrl:1
	v_pk_fma_f32 v[64:65], v[106:107], v[80:81], v[110:111] op_sel_hi:[1,0,1]
	v_pk_fma_f32 v[66:67], v[106:107], v[80:81], v[112:113] op_sel:[0,1,0]
	v_add_f32_dpp v150, v150, v150 quad_perm:[2,3,0,1] row_mask:0xf bank_mask:0xf bound_ctrl:1
	v_pk_fma_f32 v[68:69], v[106:107], v[82:83], v[144:145] op_sel_hi:[1,0,1]
	v_pk_fma_f32 v[70:71], v[106:107], v[82:83], v[146:147] op_sel:[0,1,0]
	s_mov_b64 exec, s[34:35]
	ds_write_b32 v178, v150 offset:3584
	s_mov_b64 exec, -1
	s_waitcnt lgkmcnt(1)
; #define SC_GET(X, t) do { const float* p = rec + (t) * 320; w##X = *(const f32x4*)p; a##X = *(const f32x4*)(p + 4); b##X = *(const f32x4*)(p + 8); k##X = *(const f32x4*)(p + 12); q##X = *(const f32x4*)(p + 16); \
;                 v##X = *(const f32x4*)(VVa + (t) * 64); } while (0)
; DI void scan_phase(unsigned char* lds, const Ctx& a, const Op& d, const int variant) {
;     ...
;                 SC_GET(A, 0);
; #pragma unroll 2
;                 for (int t = 0; t < SC_T; t += 2) {
;                     SC_GET(B, t + 1);
;                     SC_STEP(A, t);
;                     if (t + 2 < SC_T) SC_GET(A, t + 2);
;                     SC_STEP(B, t + 1);
;                 }
	ds_read_b128 v[72:75], v175 offset:39680
	ds_read_b128 v[76:79], v175 offset:39696
	ds_read_b128 v[80:83], v175 offset:39712
	ds_read_b128 v[84:87], v175 offset:39728
	ds_read_b128 v[88:91], v175 offset:39744
	ds_read_b128 v[92:95], v123 offset:48896
	v_pk_mul_f32 v[106:107], v[64:65], v[44:45] op_sel_hi:[1,0]
	v_pk_mul_f32 v[108:109], v[64:65], v[56:57] op_sel_hi:[1,0]
	v_pk_fma_f32 v[106:107], v[66:67], v[44:45], v[106:107] op_sel:[0,1,0]
	v_pk_fma_f32 v[108:109], v[66:67], v[56:57], v[108:109] op_sel:[0,1,0]
	v_pk_fma_f32 v[106:107], v[68:69], v[46:47], v[106:107] op_sel_hi:[1,0,1]
	v_pk_fma_f32 v[108:109], v[68:69], v[58:59], v[108:109] op_sel_hi:[1,0,1]
	v_pk_fma_f32 v[106:107], v[70:71], v[46:47], v[106:107] op_sel:[0,1,0]
	v_pk_fma_f32 v[108:109], v[70:71], v[58:59], v[108:109] op_sel:[0,1,0]
	v_pk_mul_f32 v[110:111], v[64:65], v[40:41] op_sel_hi:[1,0]
	v_add_f32_dpp v106, v106, v106 quad_perm:[1,0,3,2] row_mask:0xf bank_mask:0xf bound_ctrl:1
	v_add_f32_dpp v107, v107, v107 quad_perm:[1,0,3,2] row_mask:0xf bank_mask:0xf bound_ctrl:1
	v_pk_fma_f32 v[108:109], v[62:63], v[176:177], v[108:109]
	v_pk_mul_f32 v[112:113], v[66:67], v[40:41] op_sel:[0,1]
	v_add_f32_dpp v106, v106, v106 quad_perm:[2,3,0,1] row_mask:0xf bank_mask:0xf bound_ctrl:1
	v_add_f32_dpp v107, v107, v107 quad_perm:[2,3,0,1] row_mask:0xf bank_mask:0xf bound_ctrl:1
	v_add_f32_dpp v148, v108, v108 row_half_mirror row_mask:0xf bank_mask:0xf bound_ctrl:1
	v_add_f32_dpp v148, v109, v109 row_half_mirror row_mask:0xf bank_mask:0xa
	v_add_f32_dpp v106, v106, v106 row_half_mirror row_mask:0xf bank_mask:0xf bound_ctrl:1
	v_add_f32_dpp v107, v107, v107 row_half_mirror row_mask:0xf bank_mask:0xf bound_ctrl:1
	v_pk_mul_f32 v[144:145], v[68:69], v[42:43] op_sel_hi:[1,0]
	v_pk_mul_f32 v[146:147], v[70:71], v[42:43] op_sel:[0,1]
	v_add_f32_dpp v106, v106, v106 row_mirror row_mask:0xf bank_mask:0xf bound_ctrl:1
	v_add_f32_dpp v107, v107, v107 row_mirror row_mask:0xf bank_mask:0xf bound_ctrl:1
	v_pk_fma_f32 v[110:111], v[60:61], v[52:53], v[110:111] op_sel_hi:[1,0,1]
	v_pk_fma_f32 v[112:113], v[60:61], v[52:53], v[112:113] op_sel:[0,1,0]
	v_pk_fma_f32 v[144:145], v[60:61], v[54:55], v[144:145] op_sel_hi:[1,0,1]
	v_pk_fma_f32 v[146:147], v[60:61], v[54:55], v[146:147] op_sel:[0,1,0]
	v_pk_fma_f32 v[64:65], v[106:107], v[48:49], v[110:111] op_sel_hi:[1,0,1]
	v_pk_fma_f32 v[66:67], v[106:107], v[48:49], v[112:113] op_sel:[0,1,0]
	v_pk_fma_f32 v[68:69], v[106:107], v[50:51], v[144:145] op_sel_hi:[1,0,1]
	v_pk_fma_f32 v[70:71], v[106:107], v[50:51], v[146:147] op_sel:[0,1,0]
	s_waitcnt lgkmcnt(0)
	ds_read_b128 v[40:43], v175 offset:40960
	ds_read_b128 v[44:47], v175 offset:40976
	ds_read_b128 v[48:51], v175 offset:40992
	ds_read_b128 v[52:55], v175 offset:41008
	ds_read_b128 v[56:59], v175 offset:41024
	ds_read_b128 v[60:63], v123 offset:49152
	v_pk_mul_f32 v[106:107], v[64:65], v[76:77] op_sel_hi:[1,0]
	v_pk_mul_f32 v[108:109], v[64:65], v[88:89] op_sel_hi:[1,0]
	v_pk_fma_f32 v[106:107], v[66:67], v[76:77], v[106:107] op_sel:[0,1,0]
	v_pk_fma_f32 v[108:109], v[66:67], v[88:89], v[108:109] op_sel:[0,1,0]
	v_pk_fma_f32 v[106:107], v[68:69], v[78:79], v[106:107] op_sel_hi:[1,0,1]
	v_pk_fma_f32 v[108:109], v[68:69], v[90:91], v[108:109] op_sel_hi:[1,0,1]
	v_pk_fma_f32 v[106:107], v[70:71], v[78:79], v[106:107] op_sel:[0,1,0]
	v_pk_fma_f32 v[108:109], v[70:71], v[90:91], v[108:109] op_sel:[0,1,0]
	v_pk_mul_f32 v[110:111], v[64:65], v[72:73] op_sel_hi:[1,0]
	v_add_f32_dpp v106, v106, v106 quad_perm:[1,0,3,2] row_mask:0xf bank_mask:0xf bound_ctrl:1
	v_add_f32_dpp v107, v107, v107 quad_perm:[1,0,3,2] row_mask:0xf bank_mask:0xf bound_ctrl:1
	v_pk_fma_f32 v[108:109], v[94:95], v[176:177], v[108:109]
	v_pk_mul_f32 v[112:113], v[66:67], v[72:73] op_sel:[0,1]
	v_add_f32_dpp v106, v106, v106 quad_perm:[2,3,0,1] row_mask:0xf bank_mask:0xf bound_ctrl:1
	v_add_f32_dpp v107, v107, v107 quad_perm:[2,3,0,1] row_mask:0xf bank_mask:0xf bound_ctrl:1
	v_add_f32_dpp v149, v108, v108 row_half_mirror row_mask:0xf bank_mask:0xf bound_ctrl:1
	v_add_f32_dpp v149, v109, v109 row_half_mirror row_mask:0xf bank_mask:0xa
	v_add_f32_dpp v106, v106, v106 row_half_mirror row_mask:0xf bank_mask:0xf bound_ctrl:1
	v_add_f32_dpp v107, v107, v107 row_half_mirror row_mask:0xf bank_mask:0xf bound_ctrl:1
	v_pk_mul_f32 v[144:145], v[68:69], v[74:75] op_sel_hi:[1,0]
	v_pk_mul_f32 v[146:147], v[70:71], v[74:75] op_sel:[0,1]
	v_add_f32_dpp v150, v148, v148 row_ror:8 row_mask:0xf bank_mask:0xf bound_ctrl:1
	v_add_f32_dpp v150, v149, v149 row_ror:8 row_mask:0xf bank_mask:0xc
	v_add_f32_dpp v106, v106, v106 row_mirror row_mask:0xf bank_mask:0xf bound_ctrl:1
	v_add_f32_dpp v107, v107, v107 row_mirror row_mask:0xf bank_mask:0xf bound_ctrl:1
	v_pk_fma_f32 v[110:111], v[92:93], v[84:85], v[110:111] op_sel_hi:[1,0,1]
	v_pk_fma_f32 v[112:113], v[92:93], v[84:85], v[112:113] op_sel:[0,1,0]
	v_pk_fma_f32 v[144:145], v[92:93], v[86:87], v[144:145] op_sel_hi:[1,0,1]
	v_pk_fma_f32 v[146:147], v[92:93], v[86:87], v[146:147] op_sel:[0,1,0]
	v_add_f32_dpp v150, v150, v150 quad_perm:[1,0,3,2] row_mask:0xf bank_mask:0xf bound_ctrl:1
	v_pk_fma_f32 v[64:65], v[106:107], v[80:81], v[110:111] op_sel_hi:[1,0,1]
	v_pk_fma_f32 v[66:67], v[106:107], v[80:81], v[112:113] op_sel:[0,1,0]
	v_add_f32_dpp v150, v150, v150 quad_perm:[2,3,0,1] row_mask:0xf bank_mask:0xf bound_ctrl:1
	v_pk_fma_f32 v[68:69], v[106:107], v[82:83], v[144:145] op_sel_hi:[1,0,1]
	v_pk_fma_f32 v[70:71], v[106:107], v[82:83], v[146:147] op_sel:[0,1,0]
	s_mov_b64 exec, s[34:35]
	ds_write_b32 v178, v150 offset:3840
	s_mov_b64 exec, -1
	s_setprio 0

; DI float sigmoidf_(float x) { return 1.0f / (1.0f + __expf(-x)); }
;     template <int W  > DI void flat_body(const f32x4 (&acc)[2][2][4][2], const int row0, const int col0) const {
; #pragma unroll
;         for (int bj = 0; bj < 2; ++bj)
; #pragma unroll
;             for (int n = 0; n < 2; ++n) {
;                 const int col = col0 + bj * HALF + n * 16;
;                 const f32x4 bv = bias ? *(const f32x4*)(bias + col) : (f32x4){0.f, 0.f, 0.f, 0.f};
; #pragma unroll
;                 for (int ai = 0; ai < 2; ++ai)
; #pragma unroll
;                     for (int m = 0; m < 4; ++m) {
;                         const size_t off = (size_t)(row0 + ai * HALF + m * 16) * ldc + col;
;                         f32x4 v = acc[ai][bj][m][n] + bv;
;                         if (W == 0) v = v + *(const f32x4*)((const float*)p1 + off);
;                         else if (W == 2) v = *(const f32x4*)((const float*)out + off) + 0.0f * v;
;                         else { v[0] = __expf(-0.60653066f * sigmoidf_(v[0])); v[1] = __expf(-0.60653066f * sigmoidf_(v[1])); v[2] = __expf(-0.60653066f * sigmoidf_(v[2])); v[3] = __expf(-0.60653066f * sigmoidf_(v[3])); }
;                         *(f32x4*)((float*)out + off) = v;
;                     }
;             }
;     }
.LresidA_nobias:
	v_mad_i64_i32 v[196:197], s[10:11], v191, s75, v[138:139]
	v_lshlrev_b64 v[196:197], 2, v[196:197]
	v_add_u32_e32 v130, 0x10, v191
	v_mad_i64_i32 v[198:199], s[10:11], v130, s75, v[138:139]
	v_lshlrev_b64 v[198:199], 2, v[198:199]
	v_add_u32_e32 v130, 0x20, v191
	v_mad_i64_i32 v[200:201], s[10:11], v130, s75, v[138:139]
	v_lshlrev_b64 v[200:201], 2, v[200:201]
	v_add_u32_e32 v130, 0x30, v191
	v_mad_i64_i32 v[202:203], s[10:11], v130, s75, v[138:139]
	v_lshlrev_b64 v[202:203], 2, v[202:203]
	v_add_u32_e32 v130, 0x80, v191
	v_mad_i64_i32 v[204:205], s[10:11], v130, s75, v[138:139]
	v_lshlrev_b64 v[204:205], 2, v[204:205]
	v_add_u32_e32 v130, 0x90, v191
	v_mad_i64_i32 v[206:207], s[10:11], v130, s75, v[138:139]
	v_lshlrev_b64 v[206:207], 2, v[206:207]
	v_add_u32_e32 v130, 0xa0, v191
	v_mad_i64_i32 v[208:209], s[10:11], v130, s75, v[138:139]
	v_lshlrev_b64 v[208:209], 2, v[208:209]
	v_add_u32_e32 v130, 0xb0, v191
	v_mad_i64_i32 v[210:211], s[10:11], v130, s75, v[138:139]
	v_lshlrev_b64 v[210:211], 2, v[210:211]
	v_lshl_add_u64 v[144:145], s[2:3], 0, v[196:197]
	global_load_dwordx4 v[146:149], v[144:145], off
	v_lshl_add_u64 v[144:145], s[2:3], 0, v[198:199]
	global_load_dwordx4 v[150:153], v[144:145], off
	v_lshl_add_u64 v[144:145], s[2:3], 0, v[200:201]
	global_load_dwordx4 v[164:167], v[144:145], off
	v_lshl_add_u64 v[144:145], s[2:3], 0, v[202:203]
	global_load_dwordx4 v[168:171], v[144:145], off
	v_lshl_add_u64 v[144:145], s[2:3], 0, v[204:205]
	global_load_dwordx4 v[172:175], v[144:145], off
	v_lshl_add_u64 v[144:145], s[2:3], 0, v[206:207]
	global_load_dwordx4 v[176:179], v[144:145], off
	v_lshl_add_u64 v[144:145], s[2:3], 0, v[208:209]
	global_load_dwordx4 v[212:215], v[144:145], off
	v_lshl_add_u64 v[144:145], s[2:3], 0, v[210:211]
	global_load_dwordx4 v[140:143], v[144:145], off
	s_waitcnt vmcnt(7)
	v_pk_add_f32 v[146:147], v[146:147], v[126:127]
	v_pk_add_f32 v[148:149], v[148:149], v[128:129]
	v_lshl_add_u64 v[216:217], s[76:77], 0, v[196:197]
	global_store_dwordx4 v[216:217], v[146:149], off
	v_lshl_add_u64 v[144:145], s[2:3], 0, v[196:197]
	global_load_dwordx4 v[146:149], v[144:145], off offset:64
	s_waitcnt vmcnt(8)
	v_pk_add_f32 v[150:151], v[150:151], v[122:123]
	v_pk_add_f32 v[152:153], v[152:153], v[124:125]
	v_lshl_add_u64 v[216:217], s[76:77], 0, v[198:199]
	global_store_dwordx4 v[216:217], v[150:153], off
	v_lshl_add_u64 v[144:145], s[2:3], 0, v[198:199]
	global_load_dwordx4 v[150:153], v[144:145], off offset:64
	s_waitcnt vmcnt(9)
	v_pk_add_f32 v[164:165], v[164:165], v[118:119]
	v_pk_add_f32 v[166:167], v[166:167], v[120:121]
	v_lshl_add_u64 v[216:217], s[76:77], 0, v[200:201]
	global_store_dwordx4 v[216:217], v[164:167], off
	v_lshl_add_u64 v[144:145], s[2:3], 0, v[200:201]
	global_load_dwordx4 v[164:167], v[144:145], off offset:64
	s_waitcnt vmcnt(10)
	v_pk_add_f32 v[168:169], v[168:169], v[114:115]
	v_pk_add_f32 v[170:171], v[170:171], v[116:117]
	v_lshl_add_u64 v[216:217], s[76:77], 0, v[202:203]
	global_store_dwordx4 v[216:217], v[168:171], off
	v_lshl_add_u64 v[144:145], s[2:3], 0, v[202:203]
	global_load_dwordx4 v[168:171], v[144:145], off offset:64
	s_waitcnt vmcnt(11)
	v_pk_add_f32 v[172:173], v[172:173], v[110:111]
	v_pk_add_f32 v[174:175], v[174:175], v[112:113]
	v_lshl_add_u64 v[216:217], s[76:77], 0, v[204:205]
	global_store_dwordx4 v[216:217], v[172:175], off
	v_lshl_add_u64 v[144:145], s[2:3], 0, v[204:205]
	global_load_dwordx4 v[172:175], v[144:145], off offset:64
	s_waitcnt vmcnt(12)
	v_pk_add_f32 v[176:177], v[176:177], v[106:107]
	v_pk_add_f32 v[178:179], v[178:179], v[108:109]
	v_lshl_add_u64 v[216:217], s[76:77], 0, v[206:207]
	global_store_dwordx4 v[216:217], v[176:179], off
	v_lshl_add_u64 v[144:145], s[2:3], 0, v[206:207]
	global_load_dwordx4 v[176:179], v[144:145], off offset:64
	s_waitcnt vmcnt(13)
	v_pk_add_f32 v[212:213], v[212:213], v[102:103]
	v_pk_add_f32 v[214:215], v[214:215], v[104:105]
	v_lshl_add_u64 v[216:217], s[76:77], 0, v[208:209]
	global_store_dwordx4 v[216:217], v[212:215], off
	v_lshl_add_u64 v[144:145], s[2:3], 0, v[208:209]
	global_load_dwordx4 v[212:215], v[144:145], off offset:64
	s_waitcnt vmcnt(14)
	v_pk_add_f32 v[140:141], v[140:141], v[98:99]
	v_pk_add_f32 v[142:143], v[142:143], v[100:101]
	v_lshl_add_u64 v[216:217], s[76:77], 0, v[210:211]
	global_store_dwordx4 v[216:217], v[140:143], off
	v_lshl_add_u64 v[144:145], s[2:3], 0, v[210:211]
	global_load_dwordx4 v[140:143], v[144:145], off offset:64
	s_waitcnt vmcnt(14)
	v_pk_add_f32 v[146:147], v[146:147], v[92:93]
	v_pk_add_f32 v[148:149], v[148:149], v[94:95]
	v_lshl_add_u64 v[216:217], s[76:77], 0, v[196:197]
	global_store_dwordx4 v[216:217], v[146:149], off offset:64
	v_lshl_add_u64 v[144:145], s[2:3], 0, v[196:197]
	global_load_dwordx4 v[146:149], v[144:145], off offset:512
	s_waitcnt vmcnt(14)
	v_pk_add_f32 v[150:151], v[150:151], v[88:89]
	v_pk_add_f32 v[152:153], v[152:153], v[90:91]
	v_lshl_add_u64 v[216:217], s[76:77], 0, v[198:199]
	global_store_dwordx4 v[216:217], v[150:153], off offset:64
	v_lshl_add_u64 v[144:145], s[2:3], 0, v[198:199]
	global_load_dwordx4 v[150:153], v[144:145], off offset:512
	s_waitcnt vmcnt(14)
	v_pk_add_f32 v[164:165], v[164:165], v[84:85]
	v_pk_add_f32 v[166:167], v[166:167], v[86:87]
	v_lshl_add_u64 v[216:217], s[76:77], 0, v[200:201]
	global_store_dwordx4 v[216:217], v[164:167], off offset:64
	v_lshl_add_u64 v[144:145], s[2:3], 0, v[200:201]
	global_load_dwordx4 v[164:167], v[144:145], off offset:512
	s_waitcnt vmcnt(14)
; DI float sigmoidf_(float x) { return 1.0f / (1.0f + __expf(-x)); }
;     template <int W  > DI void flat_body(const f32x4 (&acc)[2][2][4][2], const int row0, const int col0) const {
; #pragma unroll
;         for (int bj = 0; bj < 2; ++bj)
; #pragma unroll
;             for (int n = 0; n < 2; ++n) {
;                 const int col = col0 + bj * HALF + n * 16;
;                 const f32x4 bv = bias ? *(const f32x4*)(bias + col) : (f32x4){0.f, 0.f, 0.f, 0.f};
; #pragma unroll
;                 for (int ai = 0; ai < 2; ++ai)
; #pragma unroll
;                     for (int m = 0; m < 4; ++m) {
;                         const size_t off = (size_t)(row0 + ai * HALF + m * 16) * ldc + col;
;                         f32x4 v = acc[ai][bj][m][n] + bv;
;                         if (W == 0) v = v + *(const f32x4*)((const float*)p1 + off);
;                         else if (W == 2) v = *(const f32x4*)((const float*)out + off) + 0.0f * v;
;                         else { v[0] = __expf(-0.60653066f * sigmoidf_(v[0])); v[1] = __expf(-0.60653066f * sigmoidf_(v[1])); v[2] = __expf(-0.60653066f * sigmoidf_(v[2])); v[3] = __expf(-0.60653066f * sigmoidf_(v[3])); }
;                         *(f32x4*)((float*)out + off) = v;
;                     }
;             }
;     }
	v_pk_add_f32 v[168:169], v[168:169], v[80:81]
	v_pk_add_f32 v[170:171], v[170:171], v[82:83]
	v_lshl_add_u64 v[216:217], s[76:77], 0, v[202:203]
	global_store_dwordx4 v[216:217], v[168:171], off offset:64
	v_lshl_add_u64 v[144:145], s[2:3], 0, v[202:203]
	global_load_dwordx4 v[168:171], v[144:145], off offset:512
	s_waitcnt vmcnt(14)
	v_pk_add_f32 v[172:173], v[172:173], v[76:77]
	v_pk_add_f32 v[174:175], v[174:175], v[78:79]
	v_lshl_add_u64 v[216:217], s[76:77], 0, v[204:205]
	global_store_dwordx4 v[216:217], v[172:175], off offset:64
	v_lshl_add_u64 v[144:145], s[2:3], 0, v[204:205]
	global_load_dwordx4 v[172:175], v[144:145], off offset:512
	s_waitcnt vmcnt(14)
	v_pk_add_f32 v[176:177], v[176:177], v[72:73]
	v_pk_add_f32 v[178:179], v[178:179], v[74:75]
	v_lshl_add_u64 v[216:217], s[76:77], 0, v[206:207]
	global_store_dwordx4 v[216:217], v[176:179], off offset:64
	v_lshl_add_u64 v[144:145], s[2:3], 0, v[206:207]
	global_load_dwordx4 v[176:179], v[144:145], off offset:512
	s_waitcnt vmcnt(14)
	v_pk_add_f32 v[212:213], v[212:213], v[68:69]
	v_pk_add_f32 v[214:215], v[214:215], v[70:71]
	v_lshl_add_u64 v[216:217], s[76:77], 0, v[208:209]
	global_store_dwordx4 v[216:217], v[212:215], off offset:64
	v_lshl_add_u64 v[144:145], s[2:3], 0, v[208:209]
	global_load_dwordx4 v[212:215], v[144:145], off offset:512
	s_waitcnt vmcnt(14)
	v_pk_add_f32 v[140:141], v[140:141], v[64:65]
	v_pk_add_f32 v[142:143], v[142:143], v[66:67]
	v_lshl_add_u64 v[216:217], s[76:77], 0, v[210:211]
	global_store_dwordx4 v[216:217], v[140:143], off offset:64
	v_lshl_add_u64 v[144:145], s[2:3], 0, v[210:211]
	global_load_dwordx4 v[140:143], v[144:145], off offset:512
	s_waitcnt vmcnt(14)
	v_pk_add_f32 v[146:147], v[146:147], v[60:61]
	v_pk_add_f32 v[148:149], v[148:149], v[62:63]
	v_lshl_add_u64 v[216:217], s[76:77], 0, v[196:197]
	global_store_dwordx4 v[216:217], v[146:149], off offset:512
	v_lshl_add_u64 v[144:145], s[2:3], 0, v[196:197]
	global_load_dwordx4 v[146:149], v[144:145], off offset:576
	s_waitcnt vmcnt(14)
	v_pk_add_f32 v[150:151], v[150:151], v[56:57]
	v_pk_add_f32 v[152:153], v[152:153], v[58:59]
	v_lshl_add_u64 v[216:217], s[76:77], 0, v[198:199]
	global_store_dwordx4 v[216:217], v[150:153], off offset:512
	v_lshl_add_u64 v[144:145], s[2:3], 0, v[198:199]
	global_load_dwordx4 v[150:153], v[144:145], off offset:576
	s_waitcnt vmcnt(14)
	v_pk_add_f32 v[164:165], v[164:165], v[52:53]
	v_pk_add_f32 v[166:167], v[166:167], v[54:55]
	v_lshl_add_u64 v[216:217], s[76:77], 0, v[200:201]
	global_store_dwordx4 v[216:217], v[164:167], off offset:512
	v_lshl_add_u64 v[144:145], s[2:3], 0, v[200:201]
	global_load_dwordx4 v[164:167], v[144:145], off offset:576
	s_waitcnt vmcnt(14)
	v_pk_add_f32 v[168:169], v[168:169], v[48:49]
	v_pk_add_f32 v[170:171], v[170:171], v[50:51]
	v_lshl_add_u64 v[216:217], s[76:77], 0, v[202:203]
	global_store_dwordx4 v[216:217], v[168:171], off offset:512
	v_lshl_add_u64 v[144:145], s[2:3], 0, v[202:203]
	global_load_dwordx4 v[168:171], v[144:145], off offset:576
	s_waitcnt vmcnt(14)
	v_pk_add_f32 v[172:173], v[172:173], v[44:45]
	v_pk_add_f32 v[174:175], v[174:175], v[46:47]
	v_lshl_add_u64 v[216:217], s[76:77], 0, v[204:205]
	global_store_dwordx4 v[216:217], v[172:175], off offset:512
	v_lshl_add_u64 v[144:145], s[2:3], 0, v[204:205]
	global_load_dwordx4 v[172:175], v[144:145], off offset:576
	s_waitcnt vmcnt(14)
	v_pk_add_f32 v[176:177], v[176:177], v[40:41]
	v_pk_add_f32 v[178:179], v[178:179], v[42:43]
	v_lshl_add_u64 v[216:217], s[76:77], 0, v[206:207]
	global_store_dwordx4 v[216:217], v[176:179], off offset:512
	v_lshl_add_u64 v[144:145], s[2:3], 0, v[206:207]
	global_load_dwordx4 v[176:179], v[144:145], off offset:576
	s_waitcnt vmcnt(14)
	v_pk_add_f32 v[212:213], v[212:213], v[36:37]
	v_pk_add_f32 v[214:215], v[214:215], v[38:39]
	v_lshl_add_u64 v[216:217], s[76:77], 0, v[208:209]
	global_store_dwordx4 v[216:217], v[212:215], off offset:512
	v_lshl_add_u64 v[144:145], s[2:3], 0, v[208:209]
	global_load_dwordx4 v[212:215], v[144:145], off offset:576
	s_waitcnt vmcnt(14)
	v_pk_add_f32 v[140:141], v[140:141], v[32:33]
	v_pk_add_f32 v[142:143], v[142:143], v[34:35]
	v_lshl_add_u64 v[216:217], s[76:77], 0, v[210:211]
	global_store_dwordx4 v[216:217], v[140:143], off offset:512
	v_lshl_add_u64 v[144:145], s[2:3], 0, v[210:211]
	global_load_dwordx4 v[140:143], v[144:145], off offset:576
	s_waitcnt vmcnt(14)
	v_pk_add_f32 v[146:147], v[146:147], v[28:29]
	v_pk_add_f32 v[148:149], v[148:149], v[30:31]
	v_lshl_add_u64 v[216:217], s[76:77], 0, v[196:197]
	global_store_dwordx4 v[216:217], v[146:149], off offset:576
	s_waitcnt vmcnt(13)
	v_pk_add_f32 v[150:151], v[150:151], v[24:25]
	v_pk_add_f32 v[152:153], v[152:153], v[26:27]
	v_lshl_add_u64 v[216:217], s[76:77], 0, v[198:199]
	global_store_dwordx4 v[216:217], v[150:153], off offset:576
	s_waitcnt vmcnt(12)
	v_pk_add_f32 v[164:165], v[164:165], v[20:21]
	v_pk_add_f32 v[166:167], v[166:167], v[22:23]
	v_lshl_add_u64 v[216:217], s[76:77], 0, v[200:201]
	global_store_dwordx4 v[216:217], v[164:167], off offset:576
	s_waitcnt vmcnt(11)
	v_pk_add_f32 v[168:169], v[168:169], v[16:17]
	v_pk_add_f32 v[170:171], v[170:171], v[18:19]
	v_lshl_add_u64 v[216:217], s[76:77], 0, v[202:203]
	global_store_dwordx4 v[216:217], v[168:171], off offset:576
	s_waitcnt vmcnt(10)
	v_pk_add_f32 v[172:173], v[172:173], v[12:13]
	v_pk_add_f32 v[174:175], v[174:175], v[14:15]
	v_lshl_add_u64 v[216:217], s[76:77], 0, v[204:205]
	global_store_dwordx4 v[216:217], v[172:175], off offset:576
	s_waitcnt vmcnt(9)
	v_pk_add_f32 v[176:177], v[176:177], v[8:9]
	v_pk_add_f32 v[178:179], v[178:179], v[10:11]
	v_lshl_add_u64 v[216:217], s[76:77], 0, v[206:207]
	global_store_dwordx4 v[216:217], v[176:179], off offset:576
	s_waitcnt vmcnt(8)
	v_pk_add_f32 v[212:213], v[212:213], v[4:5]
	v_pk_add_f32 v[214:215], v[214:215], v[6:7]
	v_lshl_add_u64 v[216:217], s[76:77], 0, v[208:209]
	global_store_dwordx4 v[216:217], v[212:215], off offset:576
	s_waitcnt vmcnt(7)
	v_pk_add_f32 v[140:141], v[140:141], v[0:1]
	v_pk_add_f32 v[142:143], v[142:143], v[2:3]
	v_lshl_add_u64 v[216:217], s[76:77], 0, v[210:211]
	global_store_dwordx4 v[216:217], v[140:143], off offset:576
	s_and_b64 vcc, exec, s[40:41]
	s_mov_b64 s[10:11], -1
	s_cbranch_vccnz .LBB0_590
	s_branch .LBB0_635

; DI float sigmoidf_(float x) { return 1.0f / (1.0f + __expf(-x)); }
;     template <int W  > DI void flat_body(const f32x4 (&acc)[2][2][4][2], const int row0, const int col0) const {
; #pragma unroll
;         for (int bj = 0; bj < 2; ++bj)
; #pragma unroll
;             for (int n = 0; n < 2; ++n) {
;                 const int col = col0 + bj * HALF + n * 16;
;                 const f32x4 bv = bias ? *(const f32x4*)(bias + col) : (f32x4){0.f, 0.f, 0.f, 0.f};
; #pragma unroll
;                 for (int ai = 0; ai < 2; ++ai)
; #pragma unroll
;                     for (int m = 0; m < 4; ++m) {
;                         const size_t off = (size_t)(row0 + ai * HALF + m * 16) * ldc + col;
;                         f32x4 v = acc[ai][bj][m][n] + bv;
;                         if (W == 0) v = v + *(const f32x4*)((const float*)p1 + off);
;                         else if (W == 2) v = *(const f32x4*)((const float*)out + off) + 0.0f * v;
;                         else { v[0] = __expf(-0.60653066f * sigmoidf_(v[0])); v[1] = __expf(-0.60653066f * sigmoidf_(v[1])); v[2] = __expf(-0.60653066f * sigmoidf_(v[2])); v[3] = __expf(-0.60653066f * sigmoidf_(v[3])); }
;                         *(f32x4*)((float*)out + off) = v;
;                     }
;             }
;     }
.LresidB_nobias:
	v_mad_i64_i32 v[196:197], s[0:1], v191, s30, v[138:139]
	v_lshlrev_b64 v[196:197], 2, v[196:197]
	v_add_u32_e32 v130, 0x10, v191
	v_mad_i64_i32 v[198:199], s[0:1], v130, s30, v[138:139]
	v_lshlrev_b64 v[198:199], 2, v[198:199]
	v_add_u32_e32 v130, 0x20, v191
	v_mad_i64_i32 v[200:201], s[0:1], v130, s30, v[138:139]
	v_lshlrev_b64 v[200:201], 2, v[200:201]
	v_add_u32_e32 v130, 0x30, v191
	v_mad_i64_i32 v[202:203], s[0:1], v130, s30, v[138:139]
	v_lshlrev_b64 v[202:203], 2, v[202:203]
	v_add_u32_e32 v130, 0x80, v191
	v_mad_i64_i32 v[204:205], s[0:1], v130, s30, v[138:139]
	v_lshlrev_b64 v[204:205], 2, v[204:205]
	v_add_u32_e32 v130, 0x90, v191
	v_mad_i64_i32 v[206:207], s[0:1], v130, s30, v[138:139]
	v_lshlrev_b64 v[206:207], 2, v[206:207]
	v_add_u32_e32 v130, 0xa0, v191
	v_mad_i64_i32 v[208:209], s[0:1], v130, s30, v[138:139]
	v_lshlrev_b64 v[208:209], 2, v[208:209]
	v_add_u32_e32 v130, 0xb0, v191
	v_mad_i64_i32 v[210:211], s[0:1], v130, s30, v[138:139]
	v_lshlrev_b64 v[210:211], 2, v[210:211]
	v_lshl_add_u64 v[144:145], s[8:9], 0, v[196:197]
	global_load_dwordx4 v[146:149], v[144:145], off
	v_lshl_add_u64 v[144:145], s[8:9], 0, v[198:199]
	global_load_dwordx4 v[150:153], v[144:145], off
	v_lshl_add_u64 v[144:145], s[8:9], 0, v[200:201]
	global_load_dwordx4 v[164:167], v[144:145], off
	v_lshl_add_u64 v[144:145], s[8:9], 0, v[202:203]
	global_load_dwordx4 v[168:171], v[144:145], off
	v_lshl_add_u64 v[144:145], s[8:9], 0, v[204:205]
	global_load_dwordx4 v[172:175], v[144:145], off
	v_lshl_add_u64 v[144:145], s[8:9], 0, v[206:207]
	global_load_dwordx4 v[176:179], v[144:145], off
	v_lshl_add_u64 v[144:145], s[8:9], 0, v[208:209]
	global_load_dwordx4 v[212:215], v[144:145], off
	v_lshl_add_u64 v[144:145], s[8:9], 0, v[210:211]
	global_load_dwordx4 v[140:143], v[144:145], off
	s_waitcnt vmcnt(7)
	v_pk_add_f32 v[146:147], v[146:147], v[126:127]
	v_pk_add_f32 v[148:149], v[148:149], v[128:129]
	v_lshl_add_u64 v[216:217], s[6:7], 0, v[196:197]
	global_store_dwordx4 v[216:217], v[146:149], off
	v_lshl_add_u64 v[144:145], s[8:9], 0, v[196:197]
	global_load_dwordx4 v[146:149], v[144:145], off offset:64
	s_waitcnt vmcnt(8)
	v_pk_add_f32 v[150:151], v[150:151], v[122:123]
	v_pk_add_f32 v[152:153], v[152:153], v[124:125]
	v_lshl_add_u64 v[216:217], s[6:7], 0, v[198:199]
	global_store_dwordx4 v[216:217], v[150:153], off
	v_lshl_add_u64 v[144:145], s[8:9], 0, v[198:199]
	global_load_dwordx4 v[150:153], v[144:145], off offset:64
	s_waitcnt vmcnt(9)
	v_pk_add_f32 v[164:165], v[164:165], v[118:119]
	v_pk_add_f32 v[166:167], v[166:167], v[120:121]
	v_lshl_add_u64 v[216:217], s[6:7], 0, v[200:201]
	global_store_dwordx4 v[216:217], v[164:167], off
	v_lshl_add_u64 v[144:145], s[8:9], 0, v[200:201]
	global_load_dwordx4 v[164:167], v[144:145], off offset:64
	s_waitcnt vmcnt(10)
	v_pk_add_f32 v[168:169], v[168:169], v[114:115]
	v_pk_add_f32 v[170:171], v[170:171], v[116:117]
	v_lshl_add_u64 v[216:217], s[6:7], 0, v[202:203]
	global_store_dwordx4 v[216:217], v[168:171], off
	v_lshl_add_u64 v[144:145], s[8:9], 0, v[202:203]
	global_load_dwordx4 v[168:171], v[144:145], off offset:64
	s_waitcnt vmcnt(11)
	v_pk_add_f32 v[172:173], v[172:173], v[110:111]
	v_pk_add_f32 v[174:175], v[174:175], v[112:113]
	v_lshl_add_u64 v[216:217], s[6:7], 0, v[204:205]
	global_store_dwordx4 v[216:217], v[172:175], off
	v_lshl_add_u64 v[144:145], s[8:9], 0, v[204:205]
	global_load_dwordx4 v[172:175], v[144:145], off offset:64
	s_waitcnt vmcnt(12)
	v_pk_add_f32 v[176:177], v[176:177], v[106:107]
	v_pk_add_f32 v[178:179], v[178:179], v[108:109]
	v_lshl_add_u64 v[216:217], s[6:7], 0, v[206:207]
	global_store_dwordx4 v[216:217], v[176:179], off
	v_lshl_add_u64 v[144:145], s[8:9], 0, v[206:207]
	global_load_dwordx4 v[176:179], v[144:145], off offset:64
	s_waitcnt vmcnt(13)
	v_pk_add_f32 v[212:213], v[212:213], v[102:103]
	v_pk_add_f32 v[214:215], v[214:215], v[104:105]
	v_lshl_add_u64 v[216:217], s[6:7], 0, v[208:209]
	global_store_dwordx4 v[216:217], v[212:215], off
	v_lshl_add_u64 v[144:145], s[8:9], 0, v[208:209]
	global_load_dwordx4 v[212:215], v[144:145], off offset:64
	s_waitcnt vmcnt(14)
	v_pk_add_f32 v[140:141], v[140:141], v[98:99]
	v_pk_add_f32 v[142:143], v[142:143], v[100:101]
	v_lshl_add_u64 v[216:217], s[6:7], 0, v[210:211]
	global_store_dwordx4 v[216:217], v[140:143], off
	v_lshl_add_u64 v[144:145], s[8:9], 0, v[210:211]
	global_load_dwordx4 v[140:143], v[144:145], off offset:64
	s_waitcnt vmcnt(14)
	v_pk_add_f32 v[146:147], v[146:147], v[92:93]
	v_pk_add_f32 v[148:149], v[148:149], v[94:95]
	v_lshl_add_u64 v[216:217], s[6:7], 0, v[196:197]
	global_store_dwordx4 v[216:217], v[146:149], off offset:64
	v_lshl_add_u64 v[144:145], s[8:9], 0, v[196:197]
	global_load_dwordx4 v[146:149], v[144:145], off offset:512
	s_waitcnt vmcnt(14)
	v_pk_add_f32 v[150:151], v[150:151], v[88:89]
	v_pk_add_f32 v[152:153], v[152:153], v[90:91]
	v_lshl_add_u64 v[216:217], s[6:7], 0, v[198:199]
	global_store_dwordx4 v[216:217], v[150:153], off offset:64
	v_lshl_add_u64 v[144:145], s[8:9], 0, v[198:199]
	global_load_dwordx4 v[150:153], v[144:145], off offset:512
	s_waitcnt vmcnt(14)
	v_pk_add_f32 v[164:165], v[164:165], v[84:85]
	v_pk_add_f32 v[166:167], v[166:167], v[86:87]
	v_lshl_add_u64 v[216:217], s[6:7], 0, v[200:201]
	global_store_dwordx4 v[216:217], v[164:167], off offset:64
	v_lshl_add_u64 v[144:145], s[8:9], 0, v[200:201]
	global_load_dwordx4 v[164:167], v[144:145], off offset:512
	s_waitcnt vmcnt(14)
	v_pk_add_f32 v[168:169], v[168:169], v[80:81]
	v_pk_add_f32 v[170:171], v[170:171], v[82:83]
	v_lshl_add_u64 v[216:217], s[6:7], 0, v[202:203]
	global_store_dwordx4 v[216:217], v[168:171], off offset:64
	v_lshl_add_u64 v[144:145], s[8:9], 0, v[202:203]
	global_load_dwordx4 v[168:171], v[144:145], off offset:512
	s_waitcnt vmcnt(14)
; DI float sigmoidf_(float x) { return 1.0f / (1.0f + __expf(-x)); }
;     template <int W  > DI void flat_body(const f32x4 (&acc)[2][2][4][2], const int row0, const int col0) const {
; #pragma unroll
;         for (int bj = 0; bj < 2; ++bj)
; #pragma unroll
;             for (int n = 0; n < 2; ++n) {
;                 const int col = col0 + bj * HALF + n * 16;
;                 const f32x4 bv = bias ? *(const f32x4*)(bias + col) : (f32x4){0.f, 0.f, 0.f, 0.f};
; #pragma unroll
;                 for (int ai = 0; ai < 2; ++ai)
; #pragma unroll
;                     for (int m = 0; m < 4; ++m) {
;                         const size_t off = (size_t)(row0 + ai * HALF + m * 16) * ldc + col;
;                         f32x4 v = acc[ai][bj][m][n] + bv;
;                         if (W == 0) v = v + *(const f32x4*)((const float*)p1 + off);
;                         else if (W == 2) v = *(const f32x4*)((const float*)out + off) + 0.0f * v;
;                         else { v[0] = __expf(-0.60653066f * sigmoidf_(v[0])); v[1] = __expf(-0.60653066f * sigmoidf_(v[1])); v[2] = __expf(-0.60653066f * sigmoidf_(v[2])); v[3] = __expf(-0.60653066f * sigmoidf_(v[3])); }
;                         *(f32x4*)((float*)out + off) = v;
;                     }
;             }
;     }
	v_pk_add_f32 v[172:173], v[172:173], v[76:77]
	v_pk_add_f32 v[174:175], v[174:175], v[78:79]
	v_lshl_add_u64 v[216:217], s[6:7], 0, v[204:205]
	global_store_dwordx4 v[216:217], v[172:175], off offset:64
	v_lshl_add_u64 v[144:145], s[8:9], 0, v[204:205]
	global_load_dwordx4 v[172:175], v[144:145], off offset:512
	s_waitcnt vmcnt(14)
	v_pk_add_f32 v[176:177], v[176:177], v[72:73]
	v_pk_add_f32 v[178:179], v[178:179], v[74:75]
	v_lshl_add_u64 v[216:217], s[6:7], 0, v[206:207]
	global_store_dwordx4 v[216:217], v[176:179], off offset:64
	v_lshl_add_u64 v[144:145], s[8:9], 0, v[206:207]
	global_load_dwordx4 v[176:179], v[144:145], off offset:512
	s_waitcnt vmcnt(14)
	v_pk_add_f32 v[212:213], v[212:213], v[68:69]
	v_pk_add_f32 v[214:215], v[214:215], v[70:71]
	v_lshl_add_u64 v[216:217], s[6:7], 0, v[208:209]
	global_store_dwordx4 v[216:217], v[212:215], off offset:64
	v_lshl_add_u64 v[144:145], s[8:9], 0, v[208:209]
	global_load_dwordx4 v[212:215], v[144:145], off offset:512
	s_waitcnt vmcnt(14)
	v_pk_add_f32 v[140:141], v[140:141], v[64:65]
	v_pk_add_f32 v[142:143], v[142:143], v[66:67]
	v_lshl_add_u64 v[216:217], s[6:7], 0, v[210:211]
	global_store_dwordx4 v[216:217], v[140:143], off offset:64
	v_lshl_add_u64 v[144:145], s[8:9], 0, v[210:211]
	global_load_dwordx4 v[140:143], v[144:145], off offset:512
	s_waitcnt vmcnt(14)
	v_pk_add_f32 v[146:147], v[146:147], v[60:61]
	v_pk_add_f32 v[148:149], v[148:149], v[62:63]
	v_lshl_add_u64 v[216:217], s[6:7], 0, v[196:197]
	global_store_dwordx4 v[216:217], v[146:149], off offset:512
	v_lshl_add_u64 v[144:145], s[8:9], 0, v[196:197]
	global_load_dwordx4 v[146:149], v[144:145], off offset:576
	s_waitcnt vmcnt(14)
	v_pk_add_f32 v[150:151], v[150:151], v[56:57]
	v_pk_add_f32 v[152:153], v[152:153], v[58:59]
	v_lshl_add_u64 v[216:217], s[6:7], 0, v[198:199]
	global_store_dwordx4 v[216:217], v[150:153], off offset:512
	v_lshl_add_u64 v[144:145], s[8:9], 0, v[198:199]
	global_load_dwordx4 v[150:153], v[144:145], off offset:576
	s_waitcnt vmcnt(14)
	v_pk_add_f32 v[164:165], v[164:165], v[52:53]
	v_pk_add_f32 v[166:167], v[166:167], v[54:55]
	v_lshl_add_u64 v[216:217], s[6:7], 0, v[200:201]
	global_store_dwordx4 v[216:217], v[164:167], off offset:512
	v_lshl_add_u64 v[144:145], s[8:9], 0, v[200:201]
	global_load_dwordx4 v[164:167], v[144:145], off offset:576
	s_waitcnt vmcnt(14)
	v_pk_add_f32 v[168:169], v[168:169], v[48:49]
	v_pk_add_f32 v[170:171], v[170:171], v[50:51]
	v_lshl_add_u64 v[216:217], s[6:7], 0, v[202:203]
	global_store_dwordx4 v[216:217], v[168:171], off offset:512
	v_lshl_add_u64 v[144:145], s[8:9], 0, v[202:203]
	global_load_dwordx4 v[168:171], v[144:145], off offset:576
	s_waitcnt vmcnt(14)
	v_pk_add_f32 v[172:173], v[172:173], v[44:45]
	v_pk_add_f32 v[174:175], v[174:175], v[46:47]
	v_lshl_add_u64 v[216:217], s[6:7], 0, v[204:205]
	global_store_dwordx4 v[216:217], v[172:175], off offset:512
	v_lshl_add_u64 v[144:145], s[8:9], 0, v[204:205]
	global_load_dwordx4 v[172:175], v[144:145], off offset:576
	s_waitcnt vmcnt(14)
	v_pk_add_f32 v[176:177], v[176:177], v[40:41]
	v_pk_add_f32 v[178:179], v[178:179], v[42:43]
	v_lshl_add_u64 v[216:217], s[6:7], 0, v[206:207]
	global_store_dwordx4 v[216:217], v[176:179], off offset:512
	v_lshl_add_u64 v[144:145], s[8:9], 0, v[206:207]
	global_load_dwordx4 v[176:179], v[144:145], off offset:576
	s_waitcnt vmcnt(14)
	v_pk_add_f32 v[212:213], v[212:213], v[36:37]
	v_pk_add_f32 v[214:215], v[214:215], v[38:39]
	v_lshl_add_u64 v[216:217], s[6:7], 0, v[208:209]
	global_store_dwordx4 v[216:217], v[212:215], off offset:512
	v_lshl_add_u64 v[144:145], s[8:9], 0, v[208:209]
	global_load_dwordx4 v[212:215], v[144:145], off offset:576
	s_waitcnt vmcnt(14)
	v_pk_add_f32 v[140:141], v[140:141], v[32:33]
	v_pk_add_f32 v[142:143], v[142:143], v[34:35]
	v_lshl_add_u64 v[216:217], s[6:7], 0, v[210:211]
	global_store_dwordx4 v[216:217], v[140:143], off offset:512
	v_lshl_add_u64 v[144:145], s[8:9], 0, v[210:211]
	global_load_dwordx4 v[140:143], v[144:145], off offset:576
	s_waitcnt vmcnt(14)
	v_pk_add_f32 v[146:147], v[146:147], v[28:29]
	v_pk_add_f32 v[148:149], v[148:149], v[30:31]
	v_lshl_add_u64 v[216:217], s[6:7], 0, v[196:197]
	global_store_dwordx4 v[216:217], v[146:149], off offset:576
	s_waitcnt vmcnt(13)
	v_pk_add_f32 v[150:151], v[150:151], v[24:25]
	v_pk_add_f32 v[152:153], v[152:153], v[26:27]
	v_lshl_add_u64 v[216:217], s[6:7], 0, v[198:199]
	global_store_dwordx4 v[216:217], v[150:153], off offset:576
	s_waitcnt vmcnt(12)
	v_pk_add_f32 v[164:165], v[164:165], v[20:21]
	v_pk_add_f32 v[166:167], v[166:167], v[22:23]
	v_lshl_add_u64 v[216:217], s[6:7], 0, v[200:201]
	global_store_dwordx4 v[216:217], v[164:167], off offset:576
	s_waitcnt vmcnt(11)
	v_pk_add_f32 v[168:169], v[168:169], v[16:17]
	v_pk_add_f32 v[170:171], v[170:171], v[18:19]
	v_lshl_add_u64 v[216:217], s[6:7], 0, v[202:203]
	global_store_dwordx4 v[216:217], v[168:171], off offset:576
	s_waitcnt vmcnt(10)
	v_pk_add_f32 v[172:173], v[172:173], v[12:13]
	v_pk_add_f32 v[174:175], v[174:175], v[14:15]
	v_lshl_add_u64 v[216:217], s[6:7], 0, v[204:205]
	global_store_dwordx4 v[216:217], v[172:175], off offset:576
	s_waitcnt vmcnt(9)
	v_pk_add_f32 v[176:177], v[176:177], v[8:9]
	v_pk_add_f32 v[178:179], v[178:179], v[10:11]
	v_lshl_add_u64 v[216:217], s[6:7], 0, v[206:207]
	global_store_dwordx4 v[216:217], v[176:179], off offset:576
	s_waitcnt vmcnt(8)
	v_pk_add_f32 v[212:213], v[212:213], v[4:5]
	v_pk_add_f32 v[214:215], v[214:215], v[6:7]
	v_lshl_add_u64 v[216:217], s[6:7], 0, v[208:209]
	global_store_dwordx4 v[216:217], v[212:215], off offset:576
	s_waitcnt vmcnt(7)
	v_pk_add_f32 v[140:141], v[140:141], v[0:1]
	v_pk_add_f32 v[142:143], v[142:143], v[2:3]
	v_lshl_add_u64 v[216:217], s[6:7], 0, v[210:211]
	global_store_dwordx4 v[216:217], v[140:143], off offset:576
	s_and_b64 vcc, exec, s[38:39]
	s_mov_b64 s[0:1], -1
	s_cbranch_vccnz .LBB0_809
	s_branch .LBB0_859
